# removed the compiler-duplicated s_waitcnt lgkmcnt(0) after each inline-asm lgkmcnt(0) in the GEMM loops (24 sites); norm-partial loads of the hyena tap stage issued together
# speedup vs baseline: 1.0097x; 1.0097x over previous
; #define PG8_STAGE(bufoff, gbase, voff) do { _Pragma("unroll") for (int _i = 0; _i < 2; ++_i) \
;         __builtin_amdgcn_global_load_lds((const unsigned*)((const char*)(gbase) + (voff)[_i]), (LAS unsigned*)(lds + (bufoff) + ldsw + _i * 8192), 16, 0, 0); } while (0)
; #define PG8_LDA(dst, b, h) do { _Pragma("unroll") for (int m = 0; m < 4; ++m) _Pragma("unroll") for (int k = 0; k < 2; ++k) dst[m][k] = *(const LAS bf16x8*)(lds + PG8_SA(b, h) + aoff + m * 2048 + k * 1024); } while (0)
; #define PG8_LDB(dst, b, h) do { _Pragma("unroll") for (int n = 0; n < 2; ++n) _Pragma("unroll") for (int k = 0; k < 2; ++k) dst[n][k] = *(const LAS bf16x8*)(lds + PG8_SB(b, h) + boff + n * 2048 + k * 1024); } while (0)
; #define PG8_MMA(ai, bj, At, Bt) do { __builtin_amdgcn_s_setprio(1); _Pragma("unroll") for (int m = 0; m < 4; ++m) _Pragma("unroll") for (int n = 0; n < 2; ++n) _Pragma("unroll") for (int k = 0; k < 2; ++k) \
;         acc[ai][bj][m][n] = __builtin_amdgcn_mfma_f32_16x16x32_bf16(Bt[n][k], At[m][k], acc[ai][bj][m][n], 0, 0, 0); __builtin_amdgcn_s_setprio(0); } while (0)
; #define PG8_WAIT_V(n) asm volatile("s_waitcnt vmcnt(" #n ")" ::: "memory")
; #define PG8_BAR __builtin_amdgcn_s_barrier()
; template <class Epi, class Sched>
; __device__ __forceinline__ void gemm_phase(LAS unsigned char* lds, const Gemm g, const Sched& S, const Epi& E) {
;     ...
;         for (int t = 0; t < nt; t += 2) {
;             const bool last = (t == nt - 2);
;             const char* a1 = cA + (size_t)(t + 1) * kstep;
;             const char* a2 = last ? nA : cA + (size_t)(t + 2) * kstep; const char* b2 = last ? nB : cB + (size_t)(t + 2) * kstep;
;             const char* a3 = a2 + kstep; const char* b3 = b2 + kstep;
;             if (last && has_next) S.a_ready(nxt);
;             PG8_LDB(B0, 0, 0); PG8_SCHED; PG8_LDA(At, 0, 0); PG8_STAGE(PG8_SA(1, 1), a1 + hstep, voffA);
;             PG8_WAIT_L(8); PG8_BAR; PG8_WAIT_L(0); PG8_MMA(0, 0, At, B0); PG8_BAR; PG8_SCHED;
;             PG8_LDB(B1, 0, 1); PG8_STAGE(PG8_SB(0, 0), b2, voffB);
;             PG8_BAR; PG8_WAIT_L(0); PG8_MMA(0, 1, At, B1); PG8_BAR;
;             PG8_LDA(At, 0, 1); PG8_STAGE(PG8_SA(0, 0), a2, voffA);
;             PG8_BAR; PG8_WAIT_L(0); PG8_MMA(1, 0, At, B0); PG8_BAR; PG8_SCHED;
;             PG8_STAGE(PG8_SB(0, 1), b2 + hstep, voffB);
;             PG8_WAIT_V(6); PG8_BAR; PG8_MMA(1, 1, At, B1); PG8_BAR;
.LBB0_342:
	s_nop 0
	v_add_u32_e32 v158, s42, v147
	ds_read_b128 v[142:145], v158
	ds_read_b128 v[150:153], v158 offset:1024
	ds_read_b128 v[154:157], v158 offset:2048
	ds_read_b128 v[158:161], v158 offset:3072
	s_add_u32 s18, s16, 0xfff80080
	s_addc_u32 s19, s17, -1
	s_cmp_eq_u32 s38, 28
	s_cselect_b32 s21, s11, s19
	s_cselect_b32 s20, s34, s18
	s_cselect_b32 s19, s9, s37
	s_cselect_b32 s18, s35, s36
	v_lshl_add_u64 v[194:195], s[16:17], 0, v[138:139]
	s_add_i32 m0, s24, 0xc000
	ds_read_b128 v[162:165], v149
	ds_read_b128 v[166:169], v149 offset:1024
	ds_read_b128 v[170:173], v149 offset:2048
	ds_read_b128 v[174:177], v149 offset:3072
	ds_read_b128 v[178:181], v149 offset:4096
	ds_read_b128 v[182:185], v149 offset:5120
	ds_read_b128 v[186:189], v149 offset:6144
	ds_read_b128 v[190:193], v149 offset:7168
	global_load_lds_dwordx4 v[194:195], off
	v_lshl_add_u64 v[194:195], s[16:17], 0, v[140:141]
	s_add_i32 m0, s24, 0xe000
	s_nop 0
	global_load_lds_dwordx4 v[194:195], off
	s_waitcnt lgkmcnt(8)
	s_barrier
	s_waitcnt lgkmcnt(0)
	v_mfma_f32_16x16x32_bf16 v[126:129], v[142:145], v[162:165], v[126:129]
	v_mfma_f32_16x16x32_bf16 v[122:125], v[154:157], v[162:165], v[122:125]
	v_mfma_f32_16x16x32_bf16 v[114:117], v[142:145], v[170:173], v[114:117]
	v_mfma_f32_16x16x32_bf16 v[106:109], v[154:157], v[170:173], v[106:109]
	v_mfma_f32_16x16x32_bf16 v[98:101], v[142:145], v[178:181], v[98:101]
	v_mfma_f32_16x16x32_bf16 v[90:93], v[154:157], v[178:181], v[90:93]
	v_mfma_f32_16x16x32_bf16 v[82:85], v[142:145], v[186:189], v[82:85]
	v_mfma_f32_16x16x32_bf16 v[74:77], v[154:157], v[186:189], v[74:77]
	v_mfma_f32_16x16x32_bf16 v[126:129], v[150:153], v[166:169], v[126:129]
	v_mfma_f32_16x16x32_bf16 v[122:125], v[158:161], v[166:169], v[122:125]
	v_mfma_f32_16x16x32_bf16 v[114:117], v[150:153], v[174:177], v[114:117]
	v_mfma_f32_16x16x32_bf16 v[106:109], v[158:161], v[174:177], v[106:109]
	v_mfma_f32_16x16x32_bf16 v[98:101], v[150:153], v[182:185], v[98:101]
	v_mfma_f32_16x16x32_bf16 v[90:93], v[158:161], v[182:185], v[90:93]
	v_mfma_f32_16x16x32_bf16 v[82:85], v[150:153], v[190:193], v[82:85]
	v_mfma_f32_16x16x32_bf16 v[74:77], v[158:161], v[190:193], v[74:77]
	s_barrier
	s_add_i32 s39, 0, 0x14000
	s_add_i32 s40, s42, s23
	v_add_u32_e32 v206, s39, v147
	v_lshl_add_u64 v[210:211], s[18:19], 0, v[0:1]
	s_mov_b32 m0, s40
	ds_read_b128 v[194:197], v206
	ds_read_b128 v[198:201], v206 offset:1024
	ds_read_b128 v[202:205], v206 offset:2048
	ds_read_b128 v[206:209], v206 offset:3072
	global_load_lds_dwordx4 v[210:211], off
	v_lshl_add_u64 v[220:221], s[18:19], 0, v[130:131]
	s_add_i32 m0, s40, 0x2000
	s_nop 0
	global_load_lds_dwordx4 v[220:221], off
	s_barrier
	s_waitcnt lgkmcnt(0)
	v_mfma_f32_16x16x32_bf16 v[118:121], v[194:197], v[162:165], v[118:121]
	v_mfma_f32_16x16x32_bf16 v[110:113], v[202:205], v[162:165], v[110:113]
	v_mfma_f32_16x16x32_bf16 v[102:105], v[194:197], v[170:173], v[102:105]
	v_mfma_f32_16x16x32_bf16 v[94:97], v[202:205], v[170:173], v[94:97]
	v_mfma_f32_16x16x32_bf16 v[86:89], v[194:197], v[178:181], v[86:89]
	v_mfma_f32_16x16x32_bf16 v[78:81], v[202:205], v[178:181], v[78:81]
	v_mfma_f32_16x16x32_bf16 v[70:73], v[194:197], v[186:189], v[70:73]
	v_mfma_f32_16x16x32_bf16 v[66:69], v[202:205], v[186:189], v[66:69]
	v_mfma_f32_16x16x32_bf16 v[118:121], v[198:201], v[166:169], v[118:121]
	v_mfma_f32_16x16x32_bf16 v[110:113], v[206:209], v[166:169], v[110:113]
	v_mfma_f32_16x16x32_bf16 v[102:105], v[198:201], v[174:177], v[102:105]
	v_mfma_f32_16x16x32_bf16 v[94:97], v[206:209], v[174:177], v[94:97]
	v_mfma_f32_16x16x32_bf16 v[86:89], v[198:201], v[182:185], v[86:89]
	v_mfma_f32_16x16x32_bf16 v[78:81], v[206:209], v[182:185], v[78:81]
	v_mfma_f32_16x16x32_bf16 v[70:73], v[198:201], v[190:193], v[70:73]
	v_mfma_f32_16x16x32_bf16 v[66:69], v[206:209], v[190:193], v[66:69]
	s_mov_b32 m0, s24
	v_lshl_add_u64 v[222:223], s[20:21], 0, v[134:135]
	s_barrier
	ds_read_b128 v[162:165], v149 offset:16384
	ds_read_b128 v[166:169], v149 offset:17408
	ds_read_b128 v[170:173], v149 offset:18432
	ds_read_b128 v[174:177], v149 offset:19456
	ds_read_b128 v[178:181], v149 offset:20480
	ds_read_b128 v[182:185], v149 offset:21504
	ds_read_b128 v[186:189], v149 offset:22528
	ds_read_b128 v[190:193], v149 offset:23552
	global_load_lds_dwordx4 v[222:223], off
	v_lshl_add_u64 v[234:235], s[20:21], 0, v[132:133]
	s_mov_b32 m0, s25
	s_nop 0
	global_load_lds_dwordx4 v[234:235], off
	s_barrier
	s_waitcnt lgkmcnt(0)
	v_mfma_f32_16x16x32_bf16 v[62:65], v[142:145], v[162:165], v[62:65]
	v_mfma_f32_16x16x32_bf16 v[58:61], v[154:157], v[162:165], v[58:61]
	v_mfma_f32_16x16x32_bf16 v[50:53], v[142:145], v[170:173], v[50:53]
	v_mfma_f32_16x16x32_bf16 v[42:45], v[154:157], v[170:173], v[42:45]
	v_mfma_f32_16x16x32_bf16 v[34:37], v[142:145], v[178:181], v[34:37]
	v_mfma_f32_16x16x32_bf16 v[26:29], v[154:157], v[178:181], v[26:29]
	v_mfma_f32_16x16x32_bf16 v[18:21], v[142:145], v[186:189], v[18:21]
	v_mfma_f32_16x16x32_bf16 v[10:13], v[154:157], v[186:189], v[10:13]
	v_mfma_f32_16x16x32_bf16 v[62:65], v[150:153], v[166:169], v[62:65]
	v_mfma_f32_16x16x32_bf16 v[58:61], v[158:161], v[166:169], v[58:61]
	v_mfma_f32_16x16x32_bf16 v[50:53], v[150:153], v[174:177], v[50:53]
	v_mfma_f32_16x16x32_bf16 v[42:45], v[158:161], v[174:177], v[42:45]
	v_mfma_f32_16x16x32_bf16 v[34:37], v[150:153], v[182:185], v[34:37]
	v_mfma_f32_16x16x32_bf16 v[26:29], v[158:161], v[182:185], v[26:29]
	v_mfma_f32_16x16x32_bf16 v[18:21], v[150:153], v[190:193], v[18:21]
	v_mfma_f32_16x16x32_bf16 v[10:13], v[158:161], v[190:193], v[10:13]
	s_barrier
; #define PG8_STAGE(bufoff, gbase, voff) do { _Pragma("unroll") for (int _i = 0; _i < 2; ++_i) \
;         __builtin_amdgcn_global_load_lds((const unsigned*)((const char*)(gbase) + (voff)[_i]), (LAS unsigned*)(lds + (bufoff) + ldsw + _i * 8192), 16, 0, 0); } while (0)
; #define PG8_LDA(dst, b, h) do { _Pragma("unroll") for (int m = 0; m < 4; ++m) _Pragma("unroll") for (int k = 0; k < 2; ++k) dst[m][k] = *(const LAS bf16x8*)(lds + PG8_SA(b, h) + aoff + m * 2048 + k * 1024); } while (0)
; #define PG8_LDB(dst, b, h) do { _Pragma("unroll") for (int n = 0; n < 2; ++n) _Pragma("unroll") for (int k = 0; k < 2; ++k) dst[n][k] = *(const LAS bf16x8*)(lds + PG8_SB(b, h) + boff + n * 2048 + k * 1024); } while (0)
; #define PG8_MMA(ai, bj, At, Bt) do { __builtin_amdgcn_s_setprio(1); _Pragma("unroll") for (int m = 0; m < 4; ++m) _Pragma("unroll") for (int n = 0; n < 2; ++n) _Pragma("unroll") for (int k = 0; k < 2; ++k) \
;         acc[ai][bj][m][n] = __builtin_amdgcn_mfma_f32_16x16x32_bf16(Bt[n][k], At[m][k], acc[ai][bj][m][n], 0, 0, 0); __builtin_amdgcn_s_setprio(0); } while (0)
; #define PG8_WAIT_V(n) asm volatile("s_waitcnt vmcnt(" #n ")" ::: "memory")
; #define PG8_WAIT_L(n) asm volatile("s_waitcnt lgkmcnt(" #n ")" ::: "memory")
; #define PG8_BAR __builtin_amdgcn_s_barrier()
; #define PG8_SCHED __builtin_amdgcn_sched_barrier(0)
; template <class Epi, class Sched>
; __device__ __forceinline__ void gemm_phase(LAS unsigned char* lds, const Gemm g, const Sched& S, const Epi& E) {
;     ...
;             PG8_WAIT_V(6); PG8_BAR; PG8_MMA(1, 1, At, B1); PG8_BAR;
;             PG8_LDB(B0, 1, 0); PG8_SCHED; PG8_LDA(At, 1, 0); PG8_STAGE(PG8_SA(0, 1), a2 + hstep, voffA);
;             PG8_WAIT_L(8); PG8_BAR; PG8_WAIT_L(0); PG8_MMA(0, 0, At, B0); PG8_BAR; PG8_SCHED;
;             PG8_LDB(B1, 1, 1); PG8_STAGE(PG8_SB(1, 0), b3, voffB);
;             PG8_BAR; PG8_WAIT_L(0); PG8_MMA(0, 1, At, B1); PG8_BAR;
;             PG8_LDA(At, 1, 1); PG8_STAGE(PG8_SA(1, 0), a3, voffA);
;             PG8_BAR; PG8_WAIT_L(0); PG8_MMA(1, 0, At, B0); PG8_BAR; PG8_SCHED;
	s_add_u32 s40, s18, 0x80000
	s_addc_u32 s41, s19, 0
	s_add_i32 s39, s39, s23
	v_lshl_add_u64 v[142:143], s[40:41], 0, v[0:1]
	s_mov_b32 m0, s39
	s_nop 0
	global_load_lds_dwordx4 v[142:143], off
	v_lshl_add_u64 v[142:143], s[40:41], 0, v[130:131]
	s_add_i32 m0, s39, 0x2000
	s_nop 0
	global_load_lds_dwordx4 v[142:143], off
	s_waitcnt vmcnt(6)
	s_barrier
	v_mfma_f32_16x16x32_bf16 v[54:57], v[194:197], v[162:165], v[54:57]
	v_mfma_f32_16x16x32_bf16 v[46:49], v[202:205], v[162:165], v[46:49]
	v_mfma_f32_16x16x32_bf16 v[38:41], v[194:197], v[170:173], v[38:41]
	v_mfma_f32_16x16x32_bf16 v[30:33], v[202:205], v[170:173], v[30:33]
	v_mfma_f32_16x16x32_bf16 v[22:25], v[194:197], v[178:181], v[22:25]
	v_mfma_f32_16x16x32_bf16 v[14:17], v[202:205], v[178:181], v[14:17]
	v_mfma_f32_16x16x32_bf16 v[6:9], v[194:197], v[186:189], v[6:9]
	v_mfma_f32_16x16x32_bf16 v[2:5], v[202:205], v[186:189], v[2:5]
	v_mfma_f32_16x16x32_bf16 v[54:57], v[198:201], v[166:169], v[54:57]
	v_mfma_f32_16x16x32_bf16 v[46:49], v[206:209], v[166:169], v[46:49]
	v_mfma_f32_16x16x32_bf16 v[38:41], v[198:201], v[174:177], v[38:41]
	v_mfma_f32_16x16x32_bf16 v[30:33], v[206:209], v[174:177], v[30:33]
	v_mfma_f32_16x16x32_bf16 v[22:25], v[198:201], v[182:185], v[22:25]
	v_mfma_f32_16x16x32_bf16 v[14:17], v[206:209], v[182:185], v[14:17]
	v_mfma_f32_16x16x32_bf16 v[6:9], v[198:201], v[190:193], v[6:9]
	v_mfma_f32_16x16x32_bf16 v[2:5], v[206:209], v[190:193], v[2:5]
	s_add_i32 s39, 0, 0x18000
	v_add_u32_e32 v158, s39, v147
	s_barrier
	ds_read_b128 v[142:145], v158
	ds_read_b128 v[150:153], v158 offset:1024
	ds_read_b128 v[154:157], v158 offset:2048
	ds_read_b128 v[158:161], v158 offset:3072
	s_add_u32 s20, s20, 0x80000
	s_addc_u32 s21, s21, 0
	s_mov_b32 m0, s26
	v_lshl_add_u64 v[194:195], s[20:21], 0, v[134:135]
	ds_read_b128 v[162:165], v149 offset:32768
	ds_read_b128 v[166:169], v149 offset:33792
	ds_read_b128 v[170:173], v149 offset:34816
	ds_read_b128 v[174:177], v149 offset:35840
	ds_read_b128 v[178:181], v149 offset:36864
	ds_read_b128 v[182:185], v149 offset:37888
	ds_read_b128 v[186:189], v149 offset:38912
	ds_read_b128 v[190:193], v149 offset:39936
	global_load_lds_dwordx4 v[194:195], off
	v_lshl_add_u64 v[194:195], s[20:21], 0, v[132:133]
	s_mov_b32 m0, s27
	s_nop 0
	global_load_lds_dwordx4 v[194:195], off
	s_waitcnt lgkmcnt(8)
	s_barrier
	s_waitcnt lgkmcnt(0)
	v_mfma_f32_16x16x32_bf16 v[126:129], v[142:145], v[162:165], v[126:129]
	v_mfma_f32_16x16x32_bf16 v[122:125], v[154:157], v[162:165], v[122:125]
	v_mfma_f32_16x16x32_bf16 v[114:117], v[142:145], v[170:173], v[114:117]
	v_mfma_f32_16x16x32_bf16 v[106:109], v[154:157], v[170:173], v[106:109]
	v_mfma_f32_16x16x32_bf16 v[98:101], v[142:145], v[178:181], v[98:101]
	v_mfma_f32_16x16x32_bf16 v[90:93], v[154:157], v[178:181], v[90:93]
	v_mfma_f32_16x16x32_bf16 v[82:85], v[142:145], v[186:189], v[82:85]
	v_mfma_f32_16x16x32_bf16 v[74:77], v[154:157], v[186:189], v[74:77]
	v_mfma_f32_16x16x32_bf16 v[126:129], v[150:153], v[166:169], v[126:129]
	v_mfma_f32_16x16x32_bf16 v[122:125], v[158:161], v[166:169], v[122:125]
	v_mfma_f32_16x16x32_bf16 v[114:117], v[150:153], v[174:177], v[114:117]
	v_mfma_f32_16x16x32_bf16 v[106:109], v[158:161], v[174:177], v[106:109]
	v_mfma_f32_16x16x32_bf16 v[98:101], v[150:153], v[182:185], v[98:101]
	v_mfma_f32_16x16x32_bf16 v[90:93], v[158:161], v[182:185], v[90:93]
	v_mfma_f32_16x16x32_bf16 v[82:85], v[150:153], v[190:193], v[82:85]
	v_mfma_f32_16x16x32_bf16 v[74:77], v[158:161], v[190:193], v[74:77]
	s_barrier
	s_add_i32 s20, 0, 0x1c000
	s_add_i32 s21, s39, s23
	v_add_u32_e32 v206, s20, v147
	v_lshl_add_u64 v[210:211], v[210:211], 0, s[44:45]
	s_mov_b32 m0, s21
	ds_read_b128 v[194:197], v206
	ds_read_b128 v[198:201], v206 offset:1024
	ds_read_b128 v[202:205], v206 offset:2048
	ds_read_b128 v[206:209], v206 offset:3072
	global_load_lds_dwordx4 v[210:211], off
	v_lshl_add_u64 v[210:211], v[220:221], 0, s[44:45]
	s_add_i32 m0, s21, 0x2000
	s_nop 0
	global_load_lds_dwordx4 v[210:211], off
	s_barrier
; #define PG8_STAGE(bufoff, gbase, voff) do { _Pragma("unroll") for (int _i = 0; _i < 2; ++_i) \
;         __builtin_amdgcn_global_load_lds((const unsigned*)((const char*)(gbase) + (voff)[_i]), (LAS unsigned*)(lds + (bufoff) + ldsw + _i * 8192), 16, 0, 0); } while (0)
; #define PG8_MMA(ai, bj, At, Bt) do { __builtin_amdgcn_s_setprio(1); _Pragma("unroll") for (int m = 0; m < 4; ++m) _Pragma("unroll") for (int n = 0; n < 2; ++n) _Pragma("unroll") for (int k = 0; k < 2; ++k) \
;         acc[ai][bj][m][n] = __builtin_amdgcn_mfma_f32_16x16x32_bf16(Bt[n][k], At[m][k], acc[ai][bj][m][n], 0, 0, 0); __builtin_amdgcn_s_setprio(0); } while (0)
; #define PG8_WAIT_V(n) asm volatile("s_waitcnt vmcnt(" #n ")" ::: "memory")
; #define PG8_WAIT_L(n) asm volatile("s_waitcnt lgkmcnt(" #n ")" ::: "memory")
; #define PG8_BAR __builtin_amdgcn_s_barrier()
; #define PG8_SCHED __builtin_amdgcn_sched_barrier(0)
; template <class Epi, class Sched>
; __device__ __forceinline__ void gemm_phase(LAS unsigned char* lds, const Gemm g, const Sched& S, const Epi& E) {
;     ...
;             PG8_BAR; PG8_WAIT_L(0); PG8_MMA(1, 0, At, B0); PG8_BAR; PG8_SCHED;
;             PG8_STAGE(PG8_SB(1, 1), b3 + hstep, voffB);
;             PG8_WAIT_V(6); PG8_BAR; PG8_MMA(1, 1, At, B1); PG8_BAR;
;         }
;         E(acc, cur, wr, wc, fr, fq); S.done(cur);
;     __device__ __forceinline__ void operator()(const f32x4 (&acc)[2][2][4][2], const pg8::Unit& u, int wr, int wc, int fr, int fq) const {
;     ...
;                     if (ACT == 0) { if (u.pn == (C_G / 256) && bj == 0 && wc == 0 && fq < 2) { float* gp = gate + (size_t)row * 16 + 8 * fq; *(f32x4*)gp = v0; *(f32x4*)(gp + 4) = v1; } }
	s_waitcnt lgkmcnt(0)
	v_mfma_f32_16x16x32_bf16 v[118:121], v[194:197], v[162:165], v[118:121]
	v_mfma_f32_16x16x32_bf16 v[110:113], v[202:205], v[162:165], v[110:113]
	v_mfma_f32_16x16x32_bf16 v[102:105], v[194:197], v[170:173], v[102:105]
	v_mfma_f32_16x16x32_bf16 v[94:97], v[202:205], v[170:173], v[94:97]
	v_mfma_f32_16x16x32_bf16 v[86:89], v[194:197], v[178:181], v[86:89]
	v_mfma_f32_16x16x32_bf16 v[78:81], v[202:205], v[178:181], v[78:81]
	v_mfma_f32_16x16x32_bf16 v[70:73], v[194:197], v[186:189], v[70:73]
	v_mfma_f32_16x16x32_bf16 v[66:69], v[202:205], v[186:189], v[66:69]
	v_mfma_f32_16x16x32_bf16 v[118:121], v[198:201], v[166:169], v[118:121]
	v_mfma_f32_16x16x32_bf16 v[110:113], v[206:209], v[166:169], v[110:113]
	v_mfma_f32_16x16x32_bf16 v[102:105], v[198:201], v[174:177], v[102:105]
	v_mfma_f32_16x16x32_bf16 v[94:97], v[206:209], v[174:177], v[94:97]
	v_mfma_f32_16x16x32_bf16 v[86:89], v[198:201], v[182:185], v[86:89]
	v_mfma_f32_16x16x32_bf16 v[78:81], v[206:209], v[182:185], v[78:81]
	v_mfma_f32_16x16x32_bf16 v[70:73], v[198:201], v[190:193], v[70:73]
	v_mfma_f32_16x16x32_bf16 v[66:69], v[206:209], v[190:193], v[66:69]
	s_mov_b32 m0, s28
	v_lshl_add_u64 v[210:211], v[222:223], 0, s[44:45]
	s_barrier
	ds_read_b128 v[162:165], v149 offset:49152
	ds_read_b128 v[166:169], v149 offset:50176
	ds_read_b128 v[170:173], v149 offset:51200
	ds_read_b128 v[174:177], v149 offset:52224
	ds_read_b128 v[178:181], v149 offset:53248
	ds_read_b128 v[182:185], v149 offset:54272
	ds_read_b128 v[186:189], v149 offset:55296
	ds_read_b128 v[190:193], v149 offset:56320
	global_load_lds_dwordx4 v[210:211], off
	v_lshl_add_u64 v[210:211], v[234:235], 0, s[44:45]
	s_mov_b32 m0, s29
	s_nop 0
	global_load_lds_dwordx4 v[210:211], off
	s_barrier
	s_waitcnt lgkmcnt(0)
	v_mfma_f32_16x16x32_bf16 v[62:65], v[142:145], v[162:165], v[62:65]
	v_mfma_f32_16x16x32_bf16 v[58:61], v[154:157], v[162:165], v[58:61]
	v_mfma_f32_16x16x32_bf16 v[50:53], v[142:145], v[170:173], v[50:53]
	v_mfma_f32_16x16x32_bf16 v[42:45], v[154:157], v[170:173], v[42:45]
	v_mfma_f32_16x16x32_bf16 v[34:37], v[142:145], v[178:181], v[34:37]
	v_mfma_f32_16x16x32_bf16 v[26:29], v[154:157], v[178:181], v[26:29]
	v_mfma_f32_16x16x32_bf16 v[18:21], v[142:145], v[186:189], v[18:21]
	v_mfma_f32_16x16x32_bf16 v[10:13], v[154:157], v[186:189], v[10:13]
	v_mfma_f32_16x16x32_bf16 v[62:65], v[150:153], v[166:169], v[62:65]
	v_mfma_f32_16x16x32_bf16 v[58:61], v[158:161], v[166:169], v[58:61]
	v_mfma_f32_16x16x32_bf16 v[50:53], v[150:153], v[174:177], v[50:53]
	v_mfma_f32_16x16x32_bf16 v[42:45], v[158:161], v[174:177], v[42:45]
	v_mfma_f32_16x16x32_bf16 v[34:37], v[150:153], v[182:185], v[34:37]
	v_mfma_f32_16x16x32_bf16 v[26:29], v[158:161], v[182:185], v[26:29]
	v_mfma_f32_16x16x32_bf16 v[18:21], v[150:153], v[190:193], v[18:21]
	v_mfma_f32_16x16x32_bf16 v[10:13], v[158:161], v[190:193], v[10:13]
	s_barrier
	s_add_u32 s18, s18, 0x80080
	s_addc_u32 s19, s19, 0
	s_add_i32 s20, s20, s23
	v_lshl_add_u64 v[142:143], s[18:19], 0, v[0:1]
	s_mov_b32 m0, s20
	s_nop 0
	global_load_lds_dwordx4 v[142:143], off
	v_lshl_add_u64 v[142:143], s[18:19], 0, v[130:131]
	s_add_i32 m0, s20, 0x2000
	s_nop 0
	global_load_lds_dwordx4 v[142:143], off
	s_waitcnt vmcnt(6)
	s_barrier
	v_mfma_f32_16x16x32_bf16 v[54:57], v[194:197], v[162:165], v[54:57]
	v_mfma_f32_16x16x32_bf16 v[46:49], v[202:205], v[162:165], v[46:49]
	v_mfma_f32_16x16x32_bf16 v[38:41], v[194:197], v[170:173], v[38:41]
	v_mfma_f32_16x16x32_bf16 v[30:33], v[202:205], v[170:173], v[30:33]
	v_mfma_f32_16x16x32_bf16 v[22:25], v[194:197], v[178:181], v[22:25]
	v_mfma_f32_16x16x32_bf16 v[14:17], v[202:205], v[178:181], v[14:17]
	v_mfma_f32_16x16x32_bf16 v[6:9], v[194:197], v[186:189], v[6:9]
	v_mfma_f32_16x16x32_bf16 v[2:5], v[202:205], v[186:189], v[2:5]
	v_mfma_f32_16x16x32_bf16 v[54:57], v[198:201], v[166:169], v[54:57]
	v_mfma_f32_16x16x32_bf16 v[46:49], v[206:209], v[166:169], v[46:49]
	v_mfma_f32_16x16x32_bf16 v[38:41], v[198:201], v[174:177], v[38:41]
	v_mfma_f32_16x16x32_bf16 v[30:33], v[206:209], v[174:177], v[30:33]
	v_mfma_f32_16x16x32_bf16 v[22:25], v[198:201], v[182:185], v[22:25]
	v_mfma_f32_16x16x32_bf16 v[14:17], v[206:209], v[182:185], v[14:17]
	v_mfma_f32_16x16x32_bf16 v[6:9], v[198:201], v[190:193], v[6:9]
	v_mfma_f32_16x16x32_bf16 v[2:5], v[206:209], v[190:193], v[2:5]
	s_add_i32 s38, s38, 2
	s_add_u32 s16, s16, 0x100
	s_addc_u32 s17, s17, 0
	s_add_u32 s36, s36, 0x100
	s_addc_u32 s37, s37, 0
	s_cmp_gt_u32 s38, 29
	s_barrier
	s_cbranch_scc0 .LBB0_342
	s_cmp_eq_u32 s3, 18
	s_cselect_b64 s[16:17], -1, 0
	v_lshl_add_u32 v142, s31, 8, v146
	s_and_b64 s[16:17], s[6:7], s[16:17]
	v_ashrrev_i32_e32 v143, 31, v142
	s_and_b64 s[16:17], s[16:17], s[0:1]
	s_and_saveexec_b64 s[18:19], s[16:17]
	s_cbranch_execz .LBB0_345
	v_lshlrev_b64 v[144:145], 6, v[142:143]
	v_lshl_add_u64 v[144:145], v[136:137], 0, v[144:145]
	global_store_dwordx4 v[144:145], v[126:129], off
	global_store_dwordx4 v[144:145], v[122:125], off offset:16

; __device__ __forceinline__ bf16_t f2bf(float f) { return (bf16_t)(cvt_pk_bf16(f, 0.f) & 0xFFFFu); }
; __device__ __forceinline__ void hyena_mfma(const Params& p, int l, int item, LAS unsigned char* lds) {
;     ...
;         { float nsum = 0.f;
; #pragma unroll
;           for (int qq = 0; qq < 8; ++qq) nsum += NP[qq * 512 + ch];
;           const float inv = 1.0f / nsum; const float bias = p.in[I_HBIAS][l * 512 + ch];
; #pragma unroll
;           for (int i = 0; i < 8; ++i) { const int m = tid + i * 512; float g = 0.f;
;               if (m <= 4094) { g = FX[(size_t)(4094 - m) * 512 + ch] * inv; if (m == 2047) g += bias; }
;               const bf16_t gb = f2bf(g);
; #pragma unroll
;               for (int k = 0; k < 8; ++k) { if (m - k >= 0) GS[k * GLD + (m - k)] = gb; } }
.LBB0_490:
	v_readlane_b32 s66, v254, 22
	s_or_b32 s68, s3, s66
	v_readlane_b32 s67, v254, 23
	s_ashr_i32 s69, s68, 31
	s_lshl_b64 s[66:67], s[68:69], 2
	v_readlane_b32 s69, v254, 17
	s_add_u32 vcc_lo, s69, s66
	v_readlane_b32 s69, v254, 18
	s_addc_u32 vcc_hi, s69, s67
	s_waitcnt lgkmcnt(0)
	s_barrier
	global_load_dword v2, v1, vcc
	global_load_dword v3, v1, vcc offset:2048
	global_load_dword v100, v213, vcc
	global_load_dword v101, v213, vcc offset:2048
	global_load_dword v102, v214, vcc
	global_load_dword v103, v214, vcc offset:2048
	global_load_dword v104, v217, vcc
	global_load_dword v105, v217, vcc offset:2048
	v_readlane_b32 s69, v254, 12
	s_add_i32 s68, s68, s69
	s_ashr_i32 s69, s68, 31
	s_lshl_b64 s[68:69], s[68:69], 2
	v_readlane_b32 s72, v251, 44
	v_readlane_b32 s73, v251, 45
	s_add_u32 s68, s72, s68
	s_addc_u32 s69, s73, s69
	v_readlane_b32 s74, v251, 46
	v_readlane_b32 s75, v251, 47
	v_readlane_b32 s76, v251, 48
	v_readlane_b32 s77, v251, 49
	v_readlane_b32 s78, v251, 50
	v_readlane_b32 s79, v251, 51
	v_readlane_b32 s80, v251, 52
	v_readlane_b32 s81, v251, 53
	v_readlane_b32 s82, v251, 54
	v_readlane_b32 s83, v251, 55
	v_readlane_b32 s84, v251, 56
	v_readlane_b32 s85, v251, 57
	v_readlane_b32 s86, v251, 58
	v_readlane_b32 s87, v251, 59
	s_waitcnt vmcnt(0)
	v_add_f32_e32 v2, 0, v2
	v_add_f32_e32 v2, v2, v3
	v_add_f32_e32 v2, v2, v100
	v_add_f32_e32 v2, v2, v101
	v_add_f32_e32 v2, v2, v102
	v_add_f32_e32 v2, v2, v103
	v_add_f32_e32 v2, v2, v104
	v_add_f32_e32 v2, v2, v105
	v_div_scale_f32 v3, vcc, v2, v2, 1.0
	v_rcp_f32_e32 v4, v3
	s_nop 0
	v_fma_f32 v5, -v3, v4, 1.0
	v_fmac_f32_e32 v4, v5, v4
	v_div_scale_f32 v5, vcc, 1.0, v2, 1.0
	v_mul_f32_e32 v6, v5, v4
	v_fma_f32 v7, -v3, v6, v5
	v_fmac_f32_e32 v6, v7, v4
	v_fma_f32 v3, -v3, v6, v5
	v_div_fmas_f32 v3, v3, v4, v6
	v_div_fixup_f32 v2, v3, v2, 1.0
	global_load_dword v3, v1, s[68:69]
	v_readlane_b32 s68, v254, 13
	s_add_u32 vcc_lo, s68, s66
	v_readlane_b32 s66, v254, 14
	s_addc_u32 vcc_hi, s66, s67
	v_mov_b32_e32 v4, 0
	s_mov_b64 s[66:67], exec
	v_readlane_b32 s68, v254, 28
	v_readlane_b32 s69, v254, 29
	s_and_b64 s[68:69], s[66:67], s[68:69]
	s_mov_b64 exec, s[68:69]
	s_cbranch_execz .LBB0_492
	v_lshl_add_u64 v[4:5], vcc, 0, v[194:195]
	global_load_dword v4, v[4:5], off
	v_readlane_b32 s68, v254, 30
	v_readlane_b32 s69, v254, 31
	s_waitcnt vmcnt(0)
	v_mul_f32_e32 v5, v2, v4
	v_fma_f32 v4, v2, v4, v3
	v_cndmask_b32_e64 v4, v5, v4, s[68:69]
	v_cvt_pk_bf16_f32 v4, v4, s0

; #define PG8_STAGE(bufoff, gbase, voff) do { _Pragma("unroll") for (int _i = 0; _i < 2; ++_i) \
;         __builtin_amdgcn_global_load_lds((const unsigned*)((const char*)(gbase) + (voff)[_i]), (LAS unsigned*)(lds + (bufoff) + ldsw + _i * 8192), 16, 0, 0); } while (0)
; #define PG8_LDA(dst, b, h) do { _Pragma("unroll") for (int m = 0; m < 4; ++m) _Pragma("unroll") for (int k = 0; k < 2; ++k) dst[m][k] = *(const LAS bf16x8*)(lds + PG8_SA(b, h) + aoff + m * 2048 + k * 1024); } while (0)
; #define PG8_LDB(dst, b, h) do { _Pragma("unroll") for (int n = 0; n < 2; ++n) _Pragma("unroll") for (int k = 0; k < 2; ++k) dst[n][k] = *(const LAS bf16x8*)(lds + PG8_SB(b, h) + boff + n * 2048 + k * 1024); } while (0)
; #define PG8_MMA(ai, bj, At, Bt) do { __builtin_amdgcn_s_setprio(1); _Pragma("unroll") for (int m = 0; m < 4; ++m) _Pragma("unroll") for (int n = 0; n < 2; ++n) _Pragma("unroll") for (int k = 0; k < 2; ++k) \
;         acc[ai][bj][m][n] = __builtin_amdgcn_mfma_f32_16x16x32_bf16(Bt[n][k], At[m][k], acc[ai][bj][m][n], 0, 0, 0); __builtin_amdgcn_s_setprio(0); } while (0)
; #define PG8_WAIT_V(n) asm volatile("s_waitcnt vmcnt(" #n ")" ::: "memory")
; #define PG8_BAR __builtin_amdgcn_s_barrier()
; template <class Epi, class Sched>
; __device__ __forceinline__ void gemm_phase(LAS unsigned char* lds, const Gemm g, const Sched& S, const Epi& E) {
;     ...
;         for (int t = 0; t < nt; t += 2) {
;             const bool last = (t == nt - 2);
;             const char* a1 = cA + (size_t)(t + 1) * kstep;
;             const char* a2 = last ? nA : cA + (size_t)(t + 2) * kstep; const char* b2 = last ? nB : cB + (size_t)(t + 2) * kstep;
;             const char* a3 = a2 + kstep; const char* b3 = b2 + kstep;
;             if (last && has_next) S.a_ready(nxt);
;             PG8_LDB(B0, 0, 0); PG8_SCHED; PG8_LDA(At, 0, 0); PG8_STAGE(PG8_SA(1, 1), a1 + hstep, voffA);
;             PG8_WAIT_L(8); PG8_BAR; PG8_WAIT_L(0); PG8_MMA(0, 0, At, B0); PG8_BAR; PG8_SCHED;
;             PG8_LDB(B1, 0, 1); PG8_STAGE(PG8_SB(0, 0), b2, voffB);
;             PG8_BAR; PG8_WAIT_L(0); PG8_MMA(0, 1, At, B1); PG8_BAR;
;             PG8_LDA(At, 0, 1); PG8_STAGE(PG8_SA(0, 0), a2, voffA);
;             PG8_BAR; PG8_WAIT_L(0); PG8_MMA(1, 0, At, B0); PG8_BAR; PG8_SCHED;
;             PG8_STAGE(PG8_SB(0, 1), b2 + hstep, voffB);
;             PG8_WAIT_V(6); PG8_BAR; PG8_MMA(1, 1, At, B1); PG8_BAR;
.LBB0_1123:
	s_nop 0
	v_add_u32_e32 v0, s44, v151
	ds_read_b128 v[138:141], v0
	ds_read_b128 v[142:145], v0 offset:1024
	ds_read_b128 v[146:149], v0 offset:2048
	ds_read_b128 v[154:157], v0 offset:3072
	s_add_u32 s20, s18, 0x100
	s_addc_u32 s21, s19, 0
	s_cmp_eq_u32 s42, 28
	s_cselect_b32 s25, s3, s21
	s_cselect_b32 s24, s9, s20
	s_cselect_b32 s23, s1, s41
	s_cselect_b32 s22, s15, s17
	v_lshl_add_u64 v[190:191], s[18:19], 0, v[134:135]
	s_add_i32 m0, s31, 0xc000
	ds_read_b128 v[158:161], v153
	ds_read_b128 v[162:165], v153 offset:1024
	ds_read_b128 v[166:169], v153 offset:2048
	ds_read_b128 v[170:173], v153 offset:3072
	ds_read_b128 v[174:177], v153 offset:4096
	ds_read_b128 v[178:181], v153 offset:5120
	ds_read_b128 v[182:185], v153 offset:6144
	ds_read_b128 v[186:189], v153 offset:7168
	global_load_lds_dwordx4 v[190:191], off
	v_lshl_add_u64 v[190:191], s[18:19], 0, v[136:137]
	s_add_i32 m0, s31, 0xe000
	s_nop 0
	global_load_lds_dwordx4 v[190:191], off
	s_waitcnt lgkmcnt(8)
	s_barrier
	s_waitcnt lgkmcnt(0)
	v_mfma_f32_16x16x32_bf16 v[126:129], v[138:141], v[158:161], v[126:129]
	v_mfma_f32_16x16x32_bf16 v[122:125], v[146:149], v[158:161], v[122:125]
	v_mfma_f32_16x16x32_bf16 v[110:113], v[138:141], v[166:169], v[110:113]
	v_mfma_f32_16x16x32_bf16 v[106:109], v[146:149], v[166:169], v[106:109]
	v_mfma_f32_16x16x32_bf16 v[94:97], v[138:141], v[174:177], v[94:97]
	v_mfma_f32_16x16x32_bf16 v[90:93], v[146:149], v[174:177], v[90:93]
	v_mfma_f32_16x16x32_bf16 v[78:81], v[138:141], v[182:185], v[78:81]
	v_mfma_f32_16x16x32_bf16 v[74:77], v[146:149], v[182:185], v[74:77]
	v_mfma_f32_16x16x32_bf16 v[126:129], v[142:145], v[162:165], v[126:129]
	v_mfma_f32_16x16x32_bf16 v[122:125], v[154:157], v[162:165], v[122:125]
	v_mfma_f32_16x16x32_bf16 v[110:113], v[142:145], v[170:173], v[110:113]
	v_mfma_f32_16x16x32_bf16 v[106:109], v[154:157], v[170:173], v[106:109]
	v_mfma_f32_16x16x32_bf16 v[94:97], v[142:145], v[178:181], v[94:97]
	v_mfma_f32_16x16x32_bf16 v[90:93], v[154:157], v[178:181], v[90:93]
	v_mfma_f32_16x16x32_bf16 v[78:81], v[142:145], v[186:189], v[78:81]
	v_mfma_f32_16x16x32_bf16 v[74:77], v[154:157], v[186:189], v[74:77]
	s_barrier
	s_add_i32 s43, 0, 0x14000
	s_add_i32 s18, s44, s30
	v_add_u32_e32 v0, s43, v151
	v_lshl_add_u64 v[206:207], s[22:23], 0, v[130:131]
	s_mov_b32 m0, s18
	ds_read_b128 v[190:193], v0
	ds_read_b128 v[194:197], v0 offset:1024
	ds_read_b128 v[198:201], v0 offset:2048
	ds_read_b128 v[202:205], v0 offset:3072
	global_load_lds_dwordx4 v[206:207], off
	v_lshl_add_u64 v[208:209], s[22:23], 0, v[132:133]
	s_add_i32 m0, s18, 0x2000
	s_nop 0
	global_load_lds_dwordx4 v[208:209], off
	s_barrier
	s_waitcnt lgkmcnt(0)
	v_mfma_f32_16x16x32_bf16 v[118:121], v[190:193], v[158:161], v[118:121]
	v_mfma_f32_16x16x32_bf16 v[114:117], v[198:201], v[158:161], v[114:117]
	v_mfma_f32_16x16x32_bf16 v[102:105], v[190:193], v[166:169], v[102:105]
	v_mfma_f32_16x16x32_bf16 v[98:101], v[198:201], v[166:169], v[98:101]
	v_mfma_f32_16x16x32_bf16 v[86:89], v[190:193], v[174:177], v[86:89]
	v_mfma_f32_16x16x32_bf16 v[82:85], v[198:201], v[174:177], v[82:85]
	v_mfma_f32_16x16x32_bf16 v[70:73], v[190:193], v[182:185], v[70:73]
	v_mfma_f32_16x16x32_bf16 v[66:69], v[198:201], v[182:185], v[66:69]
	v_mfma_f32_16x16x32_bf16 v[118:121], v[194:197], v[162:165], v[118:121]
	v_mfma_f32_16x16x32_bf16 v[114:117], v[202:205], v[162:165], v[114:117]
	v_mfma_f32_16x16x32_bf16 v[102:105], v[194:197], v[170:173], v[102:105]
	v_mfma_f32_16x16x32_bf16 v[98:101], v[202:205], v[170:173], v[98:101]
	v_mfma_f32_16x16x32_bf16 v[86:89], v[194:197], v[178:181], v[86:89]
	v_mfma_f32_16x16x32_bf16 v[82:85], v[202:205], v[178:181], v[82:85]
	v_mfma_f32_16x16x32_bf16 v[70:73], v[194:197], v[186:189], v[70:73]
	v_mfma_f32_16x16x32_bf16 v[66:69], v[202:205], v[186:189], v[66:69]
	s_mov_b32 m0, s31
	v_lshl_add_u64 v[210:211], s[24:25], 0, v[130:131]
	s_barrier
	ds_read_b128 v[158:161], v153 offset:16384
	ds_read_b128 v[162:165], v153 offset:17408
	ds_read_b128 v[166:169], v153 offset:18432
	ds_read_b128 v[170:173], v153 offset:19456
	ds_read_b128 v[174:177], v153 offset:20480
	ds_read_b128 v[178:181], v153 offset:21504
	ds_read_b128 v[182:185], v153 offset:22528
	ds_read_b128 v[186:189], v153 offset:23552
	global_load_lds_dwordx4 v[210:211], off
	v_lshl_add_u64 v[220:221], s[24:25], 0, v[132:133]
	s_mov_b32 m0, s34
	s_nop 0
	global_load_lds_dwordx4 v[220:221], off
	s_barrier
	s_waitcnt lgkmcnt(0)
	v_mfma_f32_16x16x32_bf16 v[62:65], v[138:141], v[158:161], v[62:65]
	v_mfma_f32_16x16x32_bf16 v[58:61], v[146:149], v[158:161], v[58:61]
	v_mfma_f32_16x16x32_bf16 v[46:49], v[138:141], v[166:169], v[46:49]
	v_mfma_f32_16x16x32_bf16 v[42:45], v[146:149], v[166:169], v[42:45]
	v_mfma_f32_16x16x32_bf16 v[30:33], v[138:141], v[174:177], v[30:33]
	v_mfma_f32_16x16x32_bf16 v[26:29], v[146:149], v[174:177], v[26:29]
	v_mfma_f32_16x16x32_bf16 v[14:17], v[138:141], v[182:185], v[14:17]
	v_mfma_f32_16x16x32_bf16 v[10:13], v[146:149], v[182:185], v[10:13]
	v_mfma_f32_16x16x32_bf16 v[62:65], v[142:145], v[162:165], v[62:65]
	v_mfma_f32_16x16x32_bf16 v[58:61], v[154:157], v[162:165], v[58:61]
	v_mfma_f32_16x16x32_bf16 v[46:49], v[142:145], v[170:173], v[46:49]
	v_mfma_f32_16x16x32_bf16 v[42:45], v[154:157], v[170:173], v[42:45]
	v_mfma_f32_16x16x32_bf16 v[30:33], v[142:145], v[178:181], v[30:33]
	v_mfma_f32_16x16x32_bf16 v[26:29], v[154:157], v[178:181], v[26:29]
	v_mfma_f32_16x16x32_bf16 v[14:17], v[142:145], v[186:189], v[14:17]
	v_mfma_f32_16x16x32_bf16 v[10:13], v[154:157], v[186:189], v[10:13]
	s_barrier
; #define PG8_STAGE(bufoff, gbase, voff) do { _Pragma("unroll") for (int _i = 0; _i < 2; ++_i) \
;         __builtin_amdgcn_global_load_lds((const unsigned*)((const char*)(gbase) + (voff)[_i]), (LAS unsigned*)(lds + (bufoff) + ldsw + _i * 8192), 16, 0, 0); } while (0)
; #define PG8_LDA(dst, b, h) do { _Pragma("unroll") for (int m = 0; m < 4; ++m) _Pragma("unroll") for (int k = 0; k < 2; ++k) dst[m][k] = *(const LAS bf16x8*)(lds + PG8_SA(b, h) + aoff + m * 2048 + k * 1024); } while (0)
; #define PG8_LDB(dst, b, h) do { _Pragma("unroll") for (int n = 0; n < 2; ++n) _Pragma("unroll") for (int k = 0; k < 2; ++k) dst[n][k] = *(const LAS bf16x8*)(lds + PG8_SB(b, h) + boff + n * 2048 + k * 1024); } while (0)
; #define PG8_MMA(ai, bj, At, Bt) do { __builtin_amdgcn_s_setprio(1); _Pragma("unroll") for (int m = 0; m < 4; ++m) _Pragma("unroll") for (int n = 0; n < 2; ++n) _Pragma("unroll") for (int k = 0; k < 2; ++k) \
;         acc[ai][bj][m][n] = __builtin_amdgcn_mfma_f32_16x16x32_bf16(Bt[n][k], At[m][k], acc[ai][bj][m][n], 0, 0, 0); __builtin_amdgcn_s_setprio(0); } while (0)
; #define PG8_WAIT_V(n) asm volatile("s_waitcnt vmcnt(" #n ")" ::: "memory")
; #define PG8_WAIT_L(n) asm volatile("s_waitcnt lgkmcnt(" #n ")" ::: "memory")
; #define PG8_BAR __builtin_amdgcn_s_barrier()
; #define PG8_SCHED __builtin_amdgcn_sched_barrier(0)
; template <class Epi, class Sched>
; __device__ __forceinline__ void gemm_phase(LAS unsigned char* lds, const Gemm g, const Sched& S, const Epi& E) {
;     ...
;             PG8_WAIT_V(6); PG8_BAR; PG8_MMA(1, 1, At, B1); PG8_BAR;
;             PG8_LDB(B0, 1, 0); PG8_SCHED; PG8_LDA(At, 1, 0); PG8_STAGE(PG8_SA(0, 1), a2 + hstep, voffA);
;             PG8_WAIT_L(8); PG8_BAR; PG8_WAIT_L(0); PG8_MMA(0, 0, At, B0); PG8_BAR; PG8_SCHED;
;             PG8_LDB(B1, 1, 1); PG8_STAGE(PG8_SB(1, 0), b3, voffB);
;             PG8_BAR; PG8_WAIT_L(0); PG8_MMA(0, 1, At, B1); PG8_BAR;
;             PG8_LDA(At, 1, 1); PG8_STAGE(PG8_SA(1, 0), a3, voffA);
;             PG8_BAR; PG8_WAIT_L(0); PG8_MMA(1, 0, At, B0); PG8_BAR; PG8_SCHED;
	s_add_u32 s18, s22, 0x80000
	s_addc_u32 s19, s23, 0
	s_add_i32 s43, s43, s30
	v_lshl_add_u64 v[138:139], s[18:19], 0, v[130:131]
	s_mov_b32 m0, s43
	s_nop 0
	global_load_lds_dwordx4 v[138:139], off
	v_lshl_add_u64 v[138:139], s[18:19], 0, v[132:133]
	s_add_i32 m0, s43, 0x2000
	s_nop 0
	global_load_lds_dwordx4 v[138:139], off
	s_waitcnt vmcnt(6)
	s_barrier
	v_mfma_f32_16x16x32_bf16 v[54:57], v[190:193], v[158:161], v[54:57]
	v_mfma_f32_16x16x32_bf16 v[50:53], v[198:201], v[158:161], v[50:53]
	v_mfma_f32_16x16x32_bf16 v[38:41], v[190:193], v[166:169], v[38:41]
	v_mfma_f32_16x16x32_bf16 v[34:37], v[198:201], v[166:169], v[34:37]
	v_mfma_f32_16x16x32_bf16 v[22:25], v[190:193], v[174:177], v[22:25]
	v_mfma_f32_16x16x32_bf16 v[18:21], v[198:201], v[174:177], v[18:21]
	v_mfma_f32_16x16x32_bf16 v[6:9], v[190:193], v[182:185], v[6:9]
	v_mfma_f32_16x16x32_bf16 v[2:5], v[198:201], v[182:185], v[2:5]
	v_mfma_f32_16x16x32_bf16 v[54:57], v[194:197], v[162:165], v[54:57]
	v_mfma_f32_16x16x32_bf16 v[50:53], v[202:205], v[162:165], v[50:53]
	v_mfma_f32_16x16x32_bf16 v[38:41], v[194:197], v[170:173], v[38:41]
	v_mfma_f32_16x16x32_bf16 v[34:37], v[202:205], v[170:173], v[34:37]
	v_mfma_f32_16x16x32_bf16 v[22:25], v[194:197], v[178:181], v[22:25]
	v_mfma_f32_16x16x32_bf16 v[18:21], v[202:205], v[178:181], v[18:21]
	v_mfma_f32_16x16x32_bf16 v[6:9], v[194:197], v[186:189], v[6:9]
	v_mfma_f32_16x16x32_bf16 v[2:5], v[202:205], v[186:189], v[2:5]
	s_add_i32 s43, 0, 0x18000
	v_add_u32_e32 v0, s43, v151
	s_barrier
	ds_read_b128 v[138:141], v0
	ds_read_b128 v[142:145], v0 offset:1024
	ds_read_b128 v[146:149], v0 offset:2048
	ds_read_b128 v[154:157], v0 offset:3072
	s_add_u32 s18, s24, 0x80000
	s_addc_u32 s19, s25, 0
	s_mov_b32 m0, s35
	v_lshl_add_u64 v[190:191], s[18:19], 0, v[130:131]
	ds_read_b128 v[158:161], v153 offset:32768
	ds_read_b128 v[162:165], v153 offset:33792
	ds_read_b128 v[166:169], v153 offset:34816
	ds_read_b128 v[170:173], v153 offset:35840
	ds_read_b128 v[174:177], v153 offset:36864
	ds_read_b128 v[178:181], v153 offset:37888
	ds_read_b128 v[182:185], v153 offset:38912
	ds_read_b128 v[186:189], v153 offset:39936
	global_load_lds_dwordx4 v[190:191], off
	v_lshl_add_u64 v[190:191], s[18:19], 0, v[132:133]
	s_mov_b32 m0, s36
	s_nop 0
	global_load_lds_dwordx4 v[190:191], off
	s_waitcnt lgkmcnt(8)
	s_barrier
	s_waitcnt lgkmcnt(0)
	v_mfma_f32_16x16x32_bf16 v[126:129], v[138:141], v[158:161], v[126:129]
	v_mfma_f32_16x16x32_bf16 v[122:125], v[146:149], v[158:161], v[122:125]
	v_mfma_f32_16x16x32_bf16 v[110:113], v[138:141], v[166:169], v[110:113]
	v_mfma_f32_16x16x32_bf16 v[106:109], v[146:149], v[166:169], v[106:109]
	v_mfma_f32_16x16x32_bf16 v[94:97], v[138:141], v[174:177], v[94:97]
	v_mfma_f32_16x16x32_bf16 v[90:93], v[146:149], v[174:177], v[90:93]
	v_mfma_f32_16x16x32_bf16 v[78:81], v[138:141], v[182:185], v[78:81]
	v_mfma_f32_16x16x32_bf16 v[74:77], v[146:149], v[182:185], v[74:77]
	v_mfma_f32_16x16x32_bf16 v[126:129], v[142:145], v[162:165], v[126:129]
	v_mfma_f32_16x16x32_bf16 v[122:125], v[154:157], v[162:165], v[122:125]
	v_mfma_f32_16x16x32_bf16 v[110:113], v[142:145], v[170:173], v[110:113]
	v_mfma_f32_16x16x32_bf16 v[106:109], v[154:157], v[170:173], v[106:109]
	v_mfma_f32_16x16x32_bf16 v[94:97], v[142:145], v[178:181], v[94:97]
	v_mfma_f32_16x16x32_bf16 v[90:93], v[154:157], v[178:181], v[90:93]
	v_mfma_f32_16x16x32_bf16 v[78:81], v[142:145], v[186:189], v[78:81]
	v_mfma_f32_16x16x32_bf16 v[74:77], v[154:157], v[186:189], v[74:77]
	s_barrier
	s_add_i32 s24, 0, 0x1c000
	s_add_i32 s18, s43, s30
	v_add_u32_e32 v0, s24, v151
	v_lshl_add_u64 v[206:207], v[206:207], 0, s[46:47]
	s_mov_b32 m0, s18
	ds_read_b128 v[190:193], v0
	ds_read_b128 v[194:197], v0 offset:1024
	ds_read_b128 v[198:201], v0 offset:2048
	ds_read_b128 v[202:205], v0 offset:3072
	global_load_lds_dwordx4 v[206:207], off
	v_lshl_add_u64 v[206:207], v[208:209], 0, s[46:47]
	s_add_i32 m0, s18, 0x2000
	s_nop 0
	global_load_lds_dwordx4 v[206:207], off
	s_barrier
	s_waitcnt lgkmcnt(0)
	v_mfma_f32_16x16x32_bf16 v[118:121], v[190:193], v[158:161], v[118:121]
	v_mfma_f32_16x16x32_bf16 v[114:117], v[198:201], v[158:161], v[114:117]
	v_mfma_f32_16x16x32_bf16 v[102:105], v[190:193], v[166:169], v[102:105]
	v_mfma_f32_16x16x32_bf16 v[98:101], v[198:201], v[166:169], v[98:101]
	v_mfma_f32_16x16x32_bf16 v[86:89], v[190:193], v[174:177], v[86:89]
	v_mfma_f32_16x16x32_bf16 v[82:85], v[198:201], v[174:177], v[82:85]
	v_mfma_f32_16x16x32_bf16 v[70:73], v[190:193], v[182:185], v[70:73]
	v_mfma_f32_16x16x32_bf16 v[66:69], v[198:201], v[182:185], v[66:69]
	v_mfma_f32_16x16x32_bf16 v[118:121], v[194:197], v[162:165], v[118:121]
	v_mfma_f32_16x16x32_bf16 v[114:117], v[202:205], v[162:165], v[114:117]
	v_mfma_f32_16x16x32_bf16 v[102:105], v[194:197], v[170:173], v[102:105]
	v_mfma_f32_16x16x32_bf16 v[98:101], v[202:205], v[170:173], v[98:101]
	v_mfma_f32_16x16x32_bf16 v[86:89], v[194:197], v[178:181], v[86:89]
	v_mfma_f32_16x16x32_bf16 v[82:85], v[202:205], v[178:181], v[82:85]
	v_mfma_f32_16x16x32_bf16 v[70:73], v[194:197], v[186:189], v[70:73]
	v_mfma_f32_16x16x32_bf16 v[66:69], v[202:205], v[186:189], v[66:69]
	s_mov_b32 m0, s38
	v_lshl_add_u64 v[206:207], v[210:211], 0, s[46:47]
	s_barrier
	ds_read_b128 v[158:161], v153 offset:49152
	ds_read_b128 v[162:165], v153 offset:50176
	ds_read_b128 v[166:169], v153 offset:51200
	ds_read_b128 v[170:173], v153 offset:52224
	ds_read_b128 v[174:177], v153 offset:53248
	ds_read_b128 v[178:181], v153 offset:54272
	ds_read_b128 v[182:185], v153 offset:55296
	ds_read_b128 v[186:189], v153 offset:56320
	global_load_lds_dwordx4 v[206:207], off
	v_lshl_add_u64 v[206:207], v[220:221], 0, s[46:47]
	s_mov_b32 m0, s39
	s_nop 0
	global_load_lds_dwordx4 v[206:207], off
	s_barrier
; #define PG8_STAGE(bufoff, gbase, voff) do { _Pragma("unroll") for (int _i = 0; _i < 2; ++_i) \
;         __builtin_amdgcn_global_load_lds((const unsigned*)((const char*)(gbase) + (voff)[_i]), (LAS unsigned*)(lds + (bufoff) + ldsw + _i * 8192), 16, 0, 0); } while (0)
; #define PG8_MMA(ai, bj, At, Bt) do { __builtin_amdgcn_s_setprio(1); _Pragma("unroll") for (int m = 0; m < 4; ++m) _Pragma("unroll") for (int n = 0; n < 2; ++n) _Pragma("unroll") for (int k = 0; k < 2; ++k) \
;         acc[ai][bj][m][n] = __builtin_amdgcn_mfma_f32_16x16x32_bf16(Bt[n][k], At[m][k], acc[ai][bj][m][n], 0, 0, 0); __builtin_amdgcn_s_setprio(0); } while (0)
; #define PG8_WAIT_V(n) asm volatile("s_waitcnt vmcnt(" #n ")" ::: "memory")
; #define PG8_WAIT_L(n) asm volatile("s_waitcnt lgkmcnt(" #n ")" ::: "memory")
; #define PG8_BAR __builtin_amdgcn_s_barrier()
; template <class Epi, class Sched>
; __device__ __forceinline__ void gemm_phase(LAS unsigned char* lds, const Gemm g, const Sched& S, const Epi& E) {
;     ...
;             PG8_BAR; PG8_WAIT_L(0); PG8_MMA(1, 0, At, B0); PG8_BAR; PG8_SCHED;
;             PG8_STAGE(PG8_SB(1, 1), b3 + hstep, voffB);
;             PG8_WAIT_V(6); PG8_BAR; PG8_MMA(1, 1, At, B1); PG8_BAR;
;         }
;         E(acc, cur, wr, wc, fr, fq); S.done(cur);
;     __device__ __forceinline__ void operator()(const f32x4 (&acc)[2][2][4][2], const pg8::Unit& u, int wr, int wc, int fr, int fq) const {
;         const int row0 = u.pm * 256 + wr * 64 + fr; const int col0 = u.pn * 256 + wc * 32 + 4 * fq;
; #pragma unroll
;         for (int ai = 0; ai < 2; ++ai)
; #pragma unroll
;             for (int m = 0; m < 4; ++m) { const int row = row0 + ai * 128 + m * 16;
;                 const float* ip; float* op; int b;
;                 if (row < ML_ROWS) { b = row >> 11; ip = xi + (size_t)row * D; op = xo + (size_t)row * D; }
;                 else { b = 8; ip = ci + (size_t)(row - ML_ROWS) * D; op = co + (size_t)(row - ML_ROWS) * D; }
;                 const float* gp = mod + (size_t)b * 12288 + slot * 2048;
; #pragma unroll
;                 for (int bj = 0; bj < 2; ++bj)
; #pragma unroll
;                     for (int n = 0; n < 2; ++n) { const int c = col0 + bj * 128 + n * 16;
;                         const f32x4 r = *(const f32x4*)(ip + c), g = *(const f32x4*)(gp + c);
;                         *(f32x4*)(op + c) = r + g * acc[ai][bj][m][n]; } }
	s_waitcnt lgkmcnt(0)
	v_mfma_f32_16x16x32_bf16 v[62:65], v[138:141], v[158:161], v[62:65]
	v_mfma_f32_16x16x32_bf16 v[58:61], v[146:149], v[158:161], v[58:61]
	v_mfma_f32_16x16x32_bf16 v[46:49], v[138:141], v[166:169], v[46:49]
	v_mfma_f32_16x16x32_bf16 v[42:45], v[146:149], v[166:169], v[42:45]
	v_mfma_f32_16x16x32_bf16 v[30:33], v[138:141], v[174:177], v[30:33]
	v_mfma_f32_16x16x32_bf16 v[26:29], v[146:149], v[174:177], v[26:29]
	v_mfma_f32_16x16x32_bf16 v[14:17], v[138:141], v[182:185], v[14:17]
	v_mfma_f32_16x16x32_bf16 v[10:13], v[146:149], v[182:185], v[10:13]
	v_mfma_f32_16x16x32_bf16 v[62:65], v[142:145], v[162:165], v[62:65]
	v_mfma_f32_16x16x32_bf16 v[58:61], v[154:157], v[162:165], v[58:61]
	v_mfma_f32_16x16x32_bf16 v[46:49], v[142:145], v[170:173], v[46:49]
	v_mfma_f32_16x16x32_bf16 v[42:45], v[154:157], v[170:173], v[42:45]
	v_mfma_f32_16x16x32_bf16 v[30:33], v[142:145], v[178:181], v[30:33]
	v_mfma_f32_16x16x32_bf16 v[26:29], v[154:157], v[178:181], v[26:29]
	v_mfma_f32_16x16x32_bf16 v[14:17], v[142:145], v[186:189], v[14:17]
	v_mfma_f32_16x16x32_bf16 v[10:13], v[154:157], v[186:189], v[10:13]
	s_barrier
	s_add_u32 s18, s22, 0x80080
	s_addc_u32 s19, s23, 0
	s_add_i32 s22, s24, s30
	v_lshl_add_u64 v[138:139], s[18:19], 0, v[130:131]
	s_mov_b32 m0, s22
	s_nop 0
	global_load_lds_dwordx4 v[138:139], off
	v_lshl_add_u64 v[138:139], s[18:19], 0, v[132:133]
	s_add_i32 m0, s22, 0x2000
	s_nop 0
	global_load_lds_dwordx4 v[138:139], off
	s_waitcnt vmcnt(6)
	s_barrier
	v_mfma_f32_16x16x32_bf16 v[54:57], v[190:193], v[158:161], v[54:57]
	v_mfma_f32_16x16x32_bf16 v[50:53], v[198:201], v[158:161], v[50:53]
	v_mfma_f32_16x16x32_bf16 v[38:41], v[190:193], v[166:169], v[38:41]
	v_mfma_f32_16x16x32_bf16 v[34:37], v[198:201], v[166:169], v[34:37]
	v_mfma_f32_16x16x32_bf16 v[22:25], v[190:193], v[174:177], v[22:25]
	v_mfma_f32_16x16x32_bf16 v[18:21], v[198:201], v[174:177], v[18:21]
	v_mfma_f32_16x16x32_bf16 v[6:9], v[190:193], v[182:185], v[6:9]
	v_mfma_f32_16x16x32_bf16 v[2:5], v[198:201], v[182:185], v[2:5]
	v_mfma_f32_16x16x32_bf16 v[54:57], v[194:197], v[162:165], v[54:57]
	v_mfma_f32_16x16x32_bf16 v[50:53], v[202:205], v[162:165], v[50:53]
	v_mfma_f32_16x16x32_bf16 v[38:41], v[194:197], v[170:173], v[38:41]
	v_mfma_f32_16x16x32_bf16 v[34:37], v[202:205], v[170:173], v[34:37]
	v_mfma_f32_16x16x32_bf16 v[22:25], v[194:197], v[178:181], v[22:25]
	v_mfma_f32_16x16x32_bf16 v[18:21], v[202:205], v[178:181], v[18:21]
	v_mfma_f32_16x16x32_bf16 v[6:9], v[194:197], v[186:189], v[6:9]
	v_mfma_f32_16x16x32_bf16 v[2:5], v[202:205], v[186:189], v[2:5]
	s_add_i32 s42, s42, 2
	s_add_u32 s17, s17, 0x100
	s_addc_u32 s41, s41, 0
	s_cmp_gt_u32 s42, 29
	s_mov_b64 s[18:19], s[20:21]
	s_barrier
	s_cbranch_scc0 .LBB0_1123
	s_lshl_b32 s1, s16, 8
	s_add_i32 s1, s1, s37
	v_readlane_b32 s44, v251, 0
	v_readlane_b32 s45, v251, 1
	v_readlane_b32 s46, v251, 2
	v_readlane_b32 s47, v251, 3
	v_readlane_b32 s48, v251, 4
	v_readlane_b32 s49, v251, 5
	v_readlane_b32 s50, v251, 6
	v_readlane_b32 s51, v251, 7
	v_readlane_b32 s22, v254, 4
	v_readlane_b32 s23, v254, 5
	v_readlane_b32 s20, v254, 6
	v_readlane_b32 s21, v254, 7
	v_readlane_b32 s18, v254, 2
	v_readlane_b32 s19, v254, 3
	s_add_i32 s3, s1, 0xffffc000
	s_ashr_i32 s15, s1, 11
	s_cmpk_lt_i32 s1, 0x4000
	s_cselect_b32 s22, s22, s20
	s_cselect_b32 s23, s23, s21
	s_cselect_b32 s20, s46, s60
	s_cselect_b32 s21, s47, s61
	s_cselect_b32 s3, s1, s3
	s_cselect_b32 s15, s15, 8
	s_mul_i32 s15, s15, 0xc000
	s_add_u32 s18, s18, s15
	s_addc_u32 s19, s19, 0
	s_add_u32 s18, s18, 0x4000
	s_addc_u32 s19, s19, 0
	v_add_u32_e32 v138, s3, v150
	v_lshl_or_b32 v139, s14, 8, v152
	v_lshlrev_b32_e32 v139, 2, v139
	v_lshl_or_b32 v138, v138, 13, v139
	v_add_u32_e32 v140, 0x20000, v138
	v_add_u32_e32 v141, 0x40000, v138
	v_add_u32_e32 v0, 0x60000, v138
	v_add_u32_e32 v210, 0x100000, v138
	v_add_u32_e32 v211, 0x120000, v138
	v_add_u32_e32 v220, 0x140000, v138
	global_load_dwordx4 v[154:157], v139, s[18:19]
	global_load_dwordx4 v[158:161], v139, s[18:19] offset:64
	global_load_dwordx4 v[162:165], v139, s[18:19] offset:512
	global_load_dwordx4 v[166:169], v139, s[18:19] offset:576
	v_add_u32_e32 v139, 0x160000, v138
	global_load_dwordx4 v[170:173], v138, s[22:23]
	global_load_dwordx4 v[174:177], v138, s[22:23] offset:64
	global_load_dwordx4 v[178:181], v138, s[22:23] offset:512
	global_load_dwordx4 v[182:185], v138, s[22:23] offset:576
	global_load_dwordx4 v[186:189], v140, s[22:23]
	global_load_dwordx4 v[190:193], v140, s[22:23] offset:64
	global_load_dwordx4 v[194:197], v140, s[22:23] offset:512
	global_load_dwordx4 v[198:201], v140, s[22:23] offset:576
	global_load_dwordx4 v[202:205], v141, s[22:23]
	global_load_dwordx4 v[206:209], v141, s[22:23] offset:64
	global_load_dwordx4 v[142:145], v141, s[22:23] offset:512
	global_load_dwordx4 v[146:149], v141, s[22:23] offset:576
	s_waitcnt vmcnt(8)
	v_pk_fma_f32 v[126:127], v[126:127], v[154:155], v[170:171]
	v_pk_fma_f32 v[128:129], v[128:129], v[156:157], v[172:173]
	v_pk_fma_f32 v[122:123], v[122:123], v[158:159], v[174:175]
	v_pk_fma_f32 v[124:125], v[124:125], v[160:161], v[176:177]
	v_pk_fma_f32 v[118:119], v[118:119], v[162:163], v[178:179]
	v_pk_fma_f32 v[120:121], v[120:121], v[164:165], v[180:181]
	v_pk_fma_f32 v[114:115], v[114:115], v[166:167], v[182:183]
	v_pk_fma_f32 v[116:117], v[116:117], v[168:169], v[184:185]
	global_store_dwordx4 v138, v[126:129], s[20:21]
	global_store_dwordx4 v138, v[122:125], s[20:21] offset:64
	global_store_dwordx4 v138, v[118:121], s[20:21] offset:512
	global_store_dwordx4 v138, v[114:117], s[20:21] offset:576
	global_load_dwordx4 v[170:173], v0, s[22:23]
	global_load_dwordx4 v[174:177], v0, s[22:23] offset:64
	global_load_dwordx4 v[178:181], v0, s[22:23] offset:512
	global_load_dwordx4 v[182:185], v0, s[22:23] offset:576
	s_waitcnt vmcnt(12)
;     __device__ __forceinline__ void operator()(const f32x4 (&acc)[2][2][4][2], const pg8::Unit& u, int wr, int wc, int fr, int fq) const {
;     ...
;             for (int m = 0; m < 4; ++m) { const int row = row0 + ai * 128 + m * 16;
;                 const float* ip; float* op; int b;
;                 if (row < ML_ROWS) { b = row >> 11; ip = xi + (size_t)row * D; op = xo + (size_t)row * D; }
;                 else { b = 8; ip = ci + (size_t)(row - ML_ROWS) * D; op = co + (size_t)(row - ML_ROWS) * D; }
;                 const float* gp = mod + (size_t)b * 12288 + slot * 2048;
; #pragma unroll
;                 for (int bj = 0; bj < 2; ++bj)
; #pragma unroll
;                     for (int n = 0; n < 2; ++n) { const int c = col0 + bj * 128 + n * 16;
;                         const f32x4 r = *(const f32x4*)(ip + c), g = *(const f32x4*)(gp + c);
;                         *(f32x4*)(op + c) = r + g * acc[ai][bj][m][n]; } }
	v_pk_fma_f32 v[110:111], v[110:111], v[154:155], v[186:187]
	v_pk_fma_f32 v[112:113], v[112:113], v[156:157], v[188:189]
	v_pk_fma_f32 v[106:107], v[106:107], v[158:159], v[190:191]
	v_pk_fma_f32 v[108:109], v[108:109], v[160:161], v[192:193]
	v_pk_fma_f32 v[102:103], v[102:103], v[162:163], v[194:195]
	v_pk_fma_f32 v[104:105], v[104:105], v[164:165], v[196:197]
	v_pk_fma_f32 v[98:99], v[98:99], v[166:167], v[198:199]
	v_pk_fma_f32 v[100:101], v[100:101], v[168:169], v[200:201]
	global_store_dwordx4 v140, v[110:113], s[20:21]
	global_store_dwordx4 v140, v[106:109], s[20:21] offset:64
	global_store_dwordx4 v140, v[102:105], s[20:21] offset:512
	global_store_dwordx4 v140, v[98:101], s[20:21] offset:576
	global_load_dwordx4 v[186:189], v210, s[22:23]
	global_load_dwordx4 v[190:193], v210, s[22:23] offset:64
	global_load_dwordx4 v[194:197], v210, s[22:23] offset:512
	global_load_dwordx4 v[198:201], v210, s[22:23] offset:576
	s_waitcnt vmcnt(16)
	v_pk_fma_f32 v[94:95], v[94:95], v[154:155], v[202:203]
	v_pk_fma_f32 v[96:97], v[96:97], v[156:157], v[204:205]
	v_pk_fma_f32 v[90:91], v[90:91], v[158:159], v[206:207]
	v_pk_fma_f32 v[92:93], v[92:93], v[160:161], v[208:209]
	v_pk_fma_f32 v[86:87], v[86:87], v[162:163], v[142:143]
	v_pk_fma_f32 v[88:89], v[88:89], v[164:165], v[144:145]
	v_pk_fma_f32 v[82:83], v[82:83], v[166:167], v[146:147]
	v_pk_fma_f32 v[84:85], v[84:85], v[168:169], v[148:149]
	global_store_dwordx4 v141, v[94:97], s[20:21]
	global_store_dwordx4 v141, v[90:93], s[20:21] offset:64
	global_store_dwordx4 v141, v[86:89], s[20:21] offset:512
	global_store_dwordx4 v141, v[82:85], s[20:21] offset:576
	global_load_dwordx4 v[202:205], v211, s[22:23]
	global_load_dwordx4 v[206:209], v211, s[22:23] offset:64
	global_load_dwordx4 v[142:145], v211, s[22:23] offset:512
	global_load_dwordx4 v[146:149], v211, s[22:23] offset:576
	s_waitcnt vmcnt(16)
	v_pk_fma_f32 v[78:79], v[78:79], v[154:155], v[170:171]
	v_pk_fma_f32 v[80:81], v[80:81], v[156:157], v[172:173]
	v_pk_fma_f32 v[74:75], v[74:75], v[158:159], v[174:175]
	v_pk_fma_f32 v[76:77], v[76:77], v[160:161], v[176:177]
	v_pk_fma_f32 v[70:71], v[70:71], v[162:163], v[178:179]
	v_pk_fma_f32 v[72:73], v[72:73], v[164:165], v[180:181]
	v_pk_fma_f32 v[66:67], v[66:67], v[166:167], v[182:183]
	v_pk_fma_f32 v[68:69], v[68:69], v[168:169], v[184:185]
	global_store_dwordx4 v0, v[78:81], s[20:21]
	global_store_dwordx4 v0, v[74:77], s[20:21] offset:64
	global_store_dwordx4 v0, v[70:73], s[20:21] offset:512
	global_store_dwordx4 v0, v[66:69], s[20:21] offset:576
	global_load_dwordx4 v[170:173], v220, s[22:23]
	global_load_dwordx4 v[174:177], v220, s[22:23] offset:64
	global_load_dwordx4 v[178:181], v220, s[22:23] offset:512
	global_load_dwordx4 v[182:185], v220, s[22:23] offset:576
	s_waitcnt vmcnt(16)
	v_pk_fma_f32 v[62:63], v[62:63], v[154:155], v[186:187]
	v_pk_fma_f32 v[64:65], v[64:65], v[156:157], v[188:189]
	v_pk_fma_f32 v[58:59], v[58:59], v[158:159], v[190:191]
	v_pk_fma_f32 v[60:61], v[60:61], v[160:161], v[192:193]
	v_pk_fma_f32 v[54:55], v[54:55], v[162:163], v[194:195]
	v_pk_fma_f32 v[56:57], v[56:57], v[164:165], v[196:197]
	v_pk_fma_f32 v[50:51], v[50:51], v[166:167], v[198:199]
	v_pk_fma_f32 v[52:53], v[52:53], v[168:169], v[200:201]
	global_store_dwordx4 v210, v[62:65], s[20:21]
	global_store_dwordx4 v210, v[58:61], s[20:21] offset:64
	global_store_dwordx4 v210, v[54:57], s[20:21] offset:512
	global_store_dwordx4 v210, v[50:53], s[20:21] offset:576
	global_load_dwordx4 v[186:189], v139, s[22:23]
	global_load_dwordx4 v[190:193], v139, s[22:23] offset:64
	global_load_dwordx4 v[194:197], v139, s[22:23] offset:512
	global_load_dwordx4 v[198:201], v139, s[22:23] offset:576
	s_waitcnt vmcnt(16)
	v_pk_fma_f32 v[46:47], v[46:47], v[154:155], v[202:203]
	v_pk_fma_f32 v[48:49], v[48:49], v[156:157], v[204:205]
	v_pk_fma_f32 v[42:43], v[42:43], v[158:159], v[206:207]
	v_pk_fma_f32 v[44:45], v[44:45], v[160:161], v[208:209]
	v_pk_fma_f32 v[38:39], v[38:39], v[162:163], v[142:143]
	v_pk_fma_f32 v[40:41], v[40:41], v[164:165], v[144:145]
	v_pk_fma_f32 v[34:35], v[34:35], v[166:167], v[146:147]
	v_pk_fma_f32 v[36:37], v[36:37], v[168:169], v[148:149]
	global_store_dwordx4 v211, v[46:49], s[20:21]
	global_store_dwordx4 v211, v[42:45], s[20:21] offset:64
	global_store_dwordx4 v211, v[38:41], s[20:21] offset:512
	global_store_dwordx4 v211, v[34:37], s[20:21] offset:576
	s_waitcnt vmcnt(12)
	v_pk_fma_f32 v[30:31], v[30:31], v[154:155], v[170:171]
	v_pk_fma_f32 v[32:33], v[32:33], v[156:157], v[172:173]
	v_pk_fma_f32 v[26:27], v[26:27], v[158:159], v[174:175]
	v_pk_fma_f32 v[28:29], v[28:29], v[160:161], v[176:177]
	v_pk_fma_f32 v[22:23], v[22:23], v[162:163], v[178:179]
	v_pk_fma_f32 v[24:25], v[24:25], v[164:165], v[180:181]
	v_pk_fma_f32 v[18:19], v[18:19], v[166:167], v[182:183]
	v_pk_fma_f32 v[20:21], v[20:21], v[168:169], v[184:185]
	global_store_dwordx4 v220, v[30:33], s[20:21]
	global_store_dwordx4 v220, v[26:29], s[20:21] offset:64
	global_store_dwordx4 v220, v[22:25], s[20:21] offset:512
	global_store_dwordx4 v220, v[18:21], s[20:21] offset:576
	s_waitcnt vmcnt(8)
	v_pk_fma_f32 v[14:15], v[14:15], v[154:155], v[186:187]
	v_pk_fma_f32 v[16:17], v[16:17], v[156:157], v[188:189]
	v_pk_fma_f32 v[10:11], v[10:11], v[158:159], v[190:191]
	v_pk_fma_f32 v[12:13], v[12:13], v[160:161], v[192:193]
	v_pk_fma_f32 v[6:7], v[6:7], v[162:163], v[194:195]
	v_pk_fma_f32 v[8:9], v[8:9], v[164:165], v[196:197]
	v_pk_fma_f32 v[2:3], v[2:3], v[166:167], v[198:199]
	v_pk_fma_f32 v[4:5], v[4:5], v[168:169], v[200:201]
	global_store_dwordx4 v139, v[14:17], s[20:21]
	global_store_dwordx4 v139, v[10:13], s[20:21] offset:64
	global_store_dwordx4 v139, v[6:9], s[20:21] offset:512
	global_store_dwordx4 v139, v[2:5], s[20:21] offset:576
	v_mov_b32_e32 v170, v219
	s_mov_b32 s14, s0
	s_mov_b32 s16, s8
	s_mov_b64 s[20:21], s[12:13]
	s_mov_b64 s[18:19], s[10:11]
	s_and_b64 vcc, exec, s[4:5]
	s_cbranch_vccnz .LBB0_1156
	s_branch .LBB0_1120

; #define PG8_STAGE(bufoff, gbase, voff) do { _Pragma("unroll") for (int _i = 0; _i < 2; ++_i) \
;         __builtin_amdgcn_global_load_lds((const unsigned*)((const char*)(gbase) + (voff)[_i]), (LAS unsigned*)(lds + (bufoff) + ldsw + _i * 8192), 16, 0, 0); } while (0)
; #define PG8_LDA(dst, b, h) do { _Pragma("unroll") for (int m = 0; m < 4; ++m) _Pragma("unroll") for (int k = 0; k < 2; ++k) dst[m][k] = *(const LAS bf16x8*)(lds + PG8_SA(b, h) + aoff + m * 2048 + k * 1024); } while (0)
; #define PG8_LDB(dst, b, h) do { _Pragma("unroll") for (int n = 0; n < 2; ++n) _Pragma("unroll") for (int k = 0; k < 2; ++k) dst[n][k] = *(const LAS bf16x8*)(lds + PG8_SB(b, h) + boff + n * 2048 + k * 1024); } while (0)
; #define PG8_MMA(ai, bj, At, Bt) do { __builtin_amdgcn_s_setprio(1); _Pragma("unroll") for (int m = 0; m < 4; ++m) _Pragma("unroll") for (int n = 0; n < 2; ++n) _Pragma("unroll") for (int k = 0; k < 2; ++k) \
;         acc[ai][bj][m][n] = __builtin_amdgcn_mfma_f32_16x16x32_bf16(Bt[n][k], At[m][k], acc[ai][bj][m][n], 0, 0, 0); __builtin_amdgcn_s_setprio(0); } while (0)
; #define PG8_WAIT_V(n) asm volatile("s_waitcnt vmcnt(" #n ")" ::: "memory")
; #define PG8_WAIT_L(n) asm volatile("s_waitcnt lgkmcnt(" #n ")" ::: "memory")
; #define PG8_BAR __builtin_amdgcn_s_barrier()
; #define PG8_SCHED __builtin_amdgcn_sched_barrier(0)
; template <class Epi, class Sched>
; __device__ __forceinline__ void gemm_phase(LAS unsigned char* lds, const Gemm g, const Sched& S, const Epi& E) {
;     ...
;             PG8_LDB(B0, 0, 0); PG8_SCHED; PG8_LDA(At, 0, 0); PG8_STAGE(PG8_SA(1, 1), a1 + hstep, voffA);
;             PG8_WAIT_L(8); PG8_BAR; PG8_WAIT_L(0); PG8_MMA(0, 0, At, B0); PG8_BAR; PG8_SCHED;
;             PG8_LDB(B1, 0, 1); PG8_STAGE(PG8_SB(0, 0), b2, voffB);
;             PG8_BAR; PG8_WAIT_L(0); PG8_MMA(0, 1, At, B1); PG8_BAR;
;             PG8_LDA(At, 0, 1); PG8_STAGE(PG8_SA(0, 0), a2, voffA);
;             PG8_BAR; PG8_WAIT_L(0); PG8_MMA(1, 0, At, B0); PG8_BAR; PG8_SCHED;
;             PG8_STAGE(PG8_SB(0, 1), b2 + hstep, voffB);
;             PG8_WAIT_V(6); PG8_BAR; PG8_MMA(1, 1, At, B1); PG8_BAR;
.LBB0_1279:
	s_nop 0
	v_add_u32_e32 v140, s47, v143
	ds_read_b128 v[146:149], v140
	ds_read_b128 v[150:153], v140 offset:1024
	ds_read_b128 v[154:157], v140 offset:2048
	ds_read_b128 v[158:161], v140 offset:3072
	s_add_u32 s22, s20, 0xfff80080
	s_addc_u32 s23, s21, -1
	s_cmp_eq_u32 s43, 28
	s_cselect_b32 s25, s3, s23
	s_cselect_b32 s24, s11, s22
	s_cselect_b32 s23, s9, s42
	s_cselect_b32 s22, s40, s41
	v_lshl_add_u64 v[140:141], s[20:21], 0, v[136:137]
	s_add_i32 m0, s17, 0xc000
	ds_read_b128 v[162:165], v145
	ds_read_b128 v[166:169], v145 offset:1024
	ds_read_b128 v[170:173], v145 offset:2048
	ds_read_b128 v[174:177], v145 offset:3072
	ds_read_b128 v[178:181], v145 offset:4096
	ds_read_b128 v[182:185], v145 offset:5120
	ds_read_b128 v[186:189], v145 offset:6144
	ds_read_b128 v[190:193], v145 offset:7168
	global_load_lds_dwordx4 v[140:141], off
	v_lshl_add_u64 v[140:141], s[20:21], 0, v[138:139]
	s_add_i32 m0, s17, 0xe000
	s_nop 0
	global_load_lds_dwordx4 v[140:141], off
	s_waitcnt lgkmcnt(8)
	s_barrier
	s_waitcnt lgkmcnt(0)
	v_mfma_f32_16x16x32_bf16 v[126:129], v[146:149], v[162:165], v[126:129]
	v_mfma_f32_16x16x32_bf16 v[122:125], v[154:157], v[162:165], v[122:125]
	v_mfma_f32_16x16x32_bf16 v[110:113], v[146:149], v[170:173], v[110:113]
	v_mfma_f32_16x16x32_bf16 v[106:109], v[154:157], v[170:173], v[106:109]
	v_mfma_f32_16x16x32_bf16 v[94:97], v[146:149], v[178:181], v[94:97]
	v_mfma_f32_16x16x32_bf16 v[90:93], v[154:157], v[178:181], v[90:93]
	v_mfma_f32_16x16x32_bf16 v[78:81], v[146:149], v[186:189], v[78:81]
	v_mfma_f32_16x16x32_bf16 v[74:77], v[154:157], v[186:189], v[74:77]
	v_mfma_f32_16x16x32_bf16 v[126:129], v[150:153], v[166:169], v[126:129]
	v_mfma_f32_16x16x32_bf16 v[122:125], v[158:161], v[166:169], v[122:125]
	v_mfma_f32_16x16x32_bf16 v[110:113], v[150:153], v[174:177], v[110:113]
	v_mfma_f32_16x16x32_bf16 v[106:109], v[158:161], v[174:177], v[106:109]
	v_mfma_f32_16x16x32_bf16 v[94:97], v[150:153], v[182:185], v[94:97]
	v_mfma_f32_16x16x32_bf16 v[90:93], v[158:161], v[182:185], v[90:93]
	v_mfma_f32_16x16x32_bf16 v[78:81], v[150:153], v[190:193], v[78:81]
	v_mfma_f32_16x16x32_bf16 v[74:77], v[158:161], v[190:193], v[74:77]
	s_barrier
	s_add_i32 s46, 0, 0x14000
	v_add_u32_e32 v140, s46, v143
	s_add_i32 s44, s47, s30
	ds_read_b128 v[194:197], v140
	ds_read_b128 v[198:201], v140 offset:1024
	ds_read_b128 v[202:205], v140 offset:2048
	ds_read_b128 v[206:209], v140 offset:3072
	v_lshl_add_u64 v[140:141], s[22:23], 0, v[0:1]
	s_mov_b32 m0, s44
	v_lshl_add_u64 v[210:211], s[22:23], 0, v[130:131]
	global_load_lds_dwordx4 v[140:141], off
	s_add_i32 m0, s44, 0x2000
	s_nop 0
	global_load_lds_dwordx4 v[210:211], off
	s_barrier
	s_waitcnt lgkmcnt(0)
	v_mfma_f32_16x16x32_bf16 v[118:121], v[194:197], v[162:165], v[118:121]
	v_mfma_f32_16x16x32_bf16 v[114:117], v[202:205], v[162:165], v[114:117]
	v_mfma_f32_16x16x32_bf16 v[102:105], v[194:197], v[170:173], v[102:105]
	v_mfma_f32_16x16x32_bf16 v[98:101], v[202:205], v[170:173], v[98:101]
	v_mfma_f32_16x16x32_bf16 v[86:89], v[194:197], v[178:181], v[86:89]
	v_mfma_f32_16x16x32_bf16 v[82:85], v[202:205], v[178:181], v[82:85]
	v_mfma_f32_16x16x32_bf16 v[70:73], v[194:197], v[186:189], v[70:73]
	v_mfma_f32_16x16x32_bf16 v[66:69], v[202:205], v[186:189], v[66:69]
	v_mfma_f32_16x16x32_bf16 v[118:121], v[198:201], v[166:169], v[118:121]
	v_mfma_f32_16x16x32_bf16 v[114:117], v[206:209], v[166:169], v[114:117]
	v_mfma_f32_16x16x32_bf16 v[102:105], v[198:201], v[174:177], v[102:105]
	v_mfma_f32_16x16x32_bf16 v[98:101], v[206:209], v[174:177], v[98:101]
	v_mfma_f32_16x16x32_bf16 v[86:89], v[198:201], v[182:185], v[86:89]
	v_mfma_f32_16x16x32_bf16 v[82:85], v[206:209], v[182:185], v[82:85]
	v_mfma_f32_16x16x32_bf16 v[70:73], v[198:201], v[190:193], v[70:73]
	v_mfma_f32_16x16x32_bf16 v[66:69], v[206:209], v[190:193], v[66:69]
	s_mov_b32 m0, s17
	v_lshl_add_u64 v[220:221], s[24:25], 0, v[134:135]
	s_barrier
	ds_read_b128 v[162:165], v145 offset:16384
	ds_read_b128 v[166:169], v145 offset:17408
	ds_read_b128 v[170:173], v145 offset:18432
	ds_read_b128 v[174:177], v145 offset:19456
	ds_read_b128 v[178:181], v145 offset:20480
	ds_read_b128 v[182:185], v145 offset:21504
	ds_read_b128 v[186:189], v145 offset:22528
	ds_read_b128 v[190:193], v145 offset:23552
	global_load_lds_dwordx4 v[220:221], off
	v_lshl_add_u64 v[222:223], s[24:25], 0, v[132:133]
	s_mov_b32 m0, s19
	s_nop 0
	global_load_lds_dwordx4 v[222:223], off
	s_barrier
	s_waitcnt lgkmcnt(0)
	v_mfma_f32_16x16x32_bf16 v[62:65], v[146:149], v[162:165], v[62:65]
	v_mfma_f32_16x16x32_bf16 v[58:61], v[154:157], v[162:165], v[58:61]
	v_mfma_f32_16x16x32_bf16 v[46:49], v[146:149], v[170:173], v[46:49]
	v_mfma_f32_16x16x32_bf16 v[42:45], v[154:157], v[170:173], v[42:45]
	v_mfma_f32_16x16x32_bf16 v[30:33], v[146:149], v[178:181], v[30:33]
	v_mfma_f32_16x16x32_bf16 v[26:29], v[154:157], v[178:181], v[26:29]
	v_mfma_f32_16x16x32_bf16 v[14:17], v[146:149], v[186:189], v[14:17]
	v_mfma_f32_16x16x32_bf16 v[10:13], v[154:157], v[186:189], v[10:13]
	v_mfma_f32_16x16x32_bf16 v[62:65], v[150:153], v[166:169], v[62:65]
	v_mfma_f32_16x16x32_bf16 v[58:61], v[158:161], v[166:169], v[58:61]
	v_mfma_f32_16x16x32_bf16 v[46:49], v[150:153], v[174:177], v[46:49]
	v_mfma_f32_16x16x32_bf16 v[42:45], v[158:161], v[174:177], v[42:45]
	v_mfma_f32_16x16x32_bf16 v[30:33], v[150:153], v[182:185], v[30:33]
	v_mfma_f32_16x16x32_bf16 v[26:29], v[158:161], v[182:185], v[26:29]
	v_mfma_f32_16x16x32_bf16 v[14:17], v[150:153], v[190:193], v[14:17]
	v_mfma_f32_16x16x32_bf16 v[10:13], v[158:161], v[190:193], v[10:13]
	s_barrier
; #define PG8_STAGE(bufoff, gbase, voff) do { _Pragma("unroll") for (int _i = 0; _i < 2; ++_i) \
;         __builtin_amdgcn_global_load_lds((const unsigned*)((const char*)(gbase) + (voff)[_i]), (LAS unsigned*)(lds + (bufoff) + ldsw + _i * 8192), 16, 0, 0); } while (0)
; #define PG8_LDA(dst, b, h) do { _Pragma("unroll") for (int m = 0; m < 4; ++m) _Pragma("unroll") for (int k = 0; k < 2; ++k) dst[m][k] = *(const LAS bf16x8*)(lds + PG8_SA(b, h) + aoff + m * 2048 + k * 1024); } while (0)
; #define PG8_LDB(dst, b, h) do { _Pragma("unroll") for (int n = 0; n < 2; ++n) _Pragma("unroll") for (int k = 0; k < 2; ++k) dst[n][k] = *(const LAS bf16x8*)(lds + PG8_SB(b, h) + boff + n * 2048 + k * 1024); } while (0)
; #define PG8_MMA(ai, bj, At, Bt) do { __builtin_amdgcn_s_setprio(1); _Pragma("unroll") for (int m = 0; m < 4; ++m) _Pragma("unroll") for (int n = 0; n < 2; ++n) _Pragma("unroll") for (int k = 0; k < 2; ++k) \
;         acc[ai][bj][m][n] = __builtin_amdgcn_mfma_f32_16x16x32_bf16(Bt[n][k], At[m][k], acc[ai][bj][m][n], 0, 0, 0); __builtin_amdgcn_s_setprio(0); } while (0)
; #define PG8_WAIT_V(n) asm volatile("s_waitcnt vmcnt(" #n ")" ::: "memory")
; #define PG8_WAIT_L(n) asm volatile("s_waitcnt lgkmcnt(" #n ")" ::: "memory")
; #define PG8_BAR __builtin_amdgcn_s_barrier()
; #define PG8_SCHED __builtin_amdgcn_sched_barrier(0)
; template <class Epi, class Sched>
; __device__ __forceinline__ void gemm_phase(LAS unsigned char* lds, const Gemm g, const Sched& S, const Epi& E) {
;     ...
;             PG8_STAGE(PG8_SB(0, 1), b2 + hstep, voffB);
;             PG8_WAIT_V(6); PG8_BAR; PG8_MMA(1, 1, At, B1); PG8_BAR;
;             PG8_LDB(B0, 1, 0); PG8_SCHED; PG8_LDA(At, 1, 0); PG8_STAGE(PG8_SA(0, 1), a2 + hstep, voffA);
;             PG8_WAIT_L(8); PG8_BAR; PG8_WAIT_L(0); PG8_MMA(0, 0, At, B0); PG8_BAR; PG8_SCHED;
;             PG8_LDB(B1, 1, 1); PG8_STAGE(PG8_SB(1, 0), b3, voffB);
;             PG8_BAR; PG8_WAIT_L(0); PG8_MMA(0, 1, At, B1); PG8_BAR;
;             PG8_LDA(At, 1, 1); PG8_STAGE(PG8_SA(1, 0), a3, voffA);
;             PG8_BAR; PG8_WAIT_L(0); PG8_MMA(1, 0, At, B0); PG8_BAR; PG8_SCHED;
	s_add_u32 s44, s22, 0x80000
	s_addc_u32 s45, s23, 0
	s_add_i32 s46, s46, s30
	v_lshl_add_u64 v[146:147], s[44:45], 0, v[0:1]
	s_mov_b32 m0, s46
	s_nop 0
	global_load_lds_dwordx4 v[146:147], off
	v_lshl_add_u64 v[146:147], s[44:45], 0, v[130:131]
	s_add_i32 m0, s46, 0x2000
	s_nop 0
	global_load_lds_dwordx4 v[146:147], off
	s_waitcnt vmcnt(6)
	s_barrier
	v_mfma_f32_16x16x32_bf16 v[54:57], v[194:197], v[162:165], v[54:57]
	v_mfma_f32_16x16x32_bf16 v[50:53], v[202:205], v[162:165], v[50:53]
	v_mfma_f32_16x16x32_bf16 v[38:41], v[194:197], v[170:173], v[38:41]
	v_mfma_f32_16x16x32_bf16 v[34:37], v[202:205], v[170:173], v[34:37]
	v_mfma_f32_16x16x32_bf16 v[22:25], v[194:197], v[178:181], v[22:25]
	v_mfma_f32_16x16x32_bf16 v[18:21], v[202:205], v[178:181], v[18:21]
	v_mfma_f32_16x16x32_bf16 v[6:9], v[194:197], v[186:189], v[6:9]
	v_mfma_f32_16x16x32_bf16 v[2:5], v[202:205], v[186:189], v[2:5]
	v_mfma_f32_16x16x32_bf16 v[54:57], v[198:201], v[166:169], v[54:57]
	v_mfma_f32_16x16x32_bf16 v[50:53], v[206:209], v[166:169], v[50:53]
	v_mfma_f32_16x16x32_bf16 v[38:41], v[198:201], v[174:177], v[38:41]
	v_mfma_f32_16x16x32_bf16 v[34:37], v[206:209], v[174:177], v[34:37]
	v_mfma_f32_16x16x32_bf16 v[22:25], v[198:201], v[182:185], v[22:25]
	v_mfma_f32_16x16x32_bf16 v[18:21], v[206:209], v[182:185], v[18:21]
	v_mfma_f32_16x16x32_bf16 v[6:9], v[198:201], v[190:193], v[6:9]
	v_mfma_f32_16x16x32_bf16 v[2:5], v[206:209], v[190:193], v[2:5]
	s_add_i32 s44, 0, 0x18000
	v_add_u32_e32 v158, s44, v143
	s_barrier
	ds_read_b128 v[146:149], v158
	ds_read_b128 v[150:153], v158 offset:1024
	ds_read_b128 v[154:157], v158 offset:2048
	ds_read_b128 v[158:161], v158 offset:3072
	s_add_u32 s24, s24, 0x80000
	s_addc_u32 s25, s25, 0
	s_mov_b32 m0, s35
	v_lshl_add_u64 v[194:195], s[24:25], 0, v[134:135]
	ds_read_b128 v[162:165], v145 offset:32768
	ds_read_b128 v[166:169], v145 offset:33792
	ds_read_b128 v[170:173], v145 offset:34816
	ds_read_b128 v[174:177], v145 offset:35840
	ds_read_b128 v[178:181], v145 offset:36864
	ds_read_b128 v[182:185], v145 offset:37888
	ds_read_b128 v[186:189], v145 offset:38912
	ds_read_b128 v[190:193], v145 offset:39936
	global_load_lds_dwordx4 v[194:195], off
	v_lshl_add_u64 v[194:195], s[24:25], 0, v[132:133]
	s_mov_b32 m0, s36
	s_nop 0
	global_load_lds_dwordx4 v[194:195], off
	s_waitcnt lgkmcnt(8)
	s_barrier
	s_waitcnt lgkmcnt(0)
	v_mfma_f32_16x16x32_bf16 v[126:129], v[146:149], v[162:165], v[126:129]
	v_mfma_f32_16x16x32_bf16 v[122:125], v[154:157], v[162:165], v[122:125]
	v_mfma_f32_16x16x32_bf16 v[110:113], v[146:149], v[170:173], v[110:113]
	v_mfma_f32_16x16x32_bf16 v[106:109], v[154:157], v[170:173], v[106:109]
	v_mfma_f32_16x16x32_bf16 v[94:97], v[146:149], v[178:181], v[94:97]
	v_mfma_f32_16x16x32_bf16 v[90:93], v[154:157], v[178:181], v[90:93]
	v_mfma_f32_16x16x32_bf16 v[78:81], v[146:149], v[186:189], v[78:81]
	v_mfma_f32_16x16x32_bf16 v[74:77], v[154:157], v[186:189], v[74:77]
	v_mfma_f32_16x16x32_bf16 v[126:129], v[150:153], v[166:169], v[126:129]
	v_mfma_f32_16x16x32_bf16 v[122:125], v[158:161], v[166:169], v[122:125]
	v_mfma_f32_16x16x32_bf16 v[110:113], v[150:153], v[174:177], v[110:113]
	v_mfma_f32_16x16x32_bf16 v[106:109], v[158:161], v[174:177], v[106:109]
	v_mfma_f32_16x16x32_bf16 v[94:97], v[150:153], v[182:185], v[94:97]
	v_mfma_f32_16x16x32_bf16 v[90:93], v[158:161], v[182:185], v[90:93]
	v_mfma_f32_16x16x32_bf16 v[78:81], v[150:153], v[190:193], v[78:81]
	v_mfma_f32_16x16x32_bf16 v[74:77], v[158:161], v[190:193], v[74:77]
	s_barrier
	s_add_i32 s24, 0, 0x1c000
	s_add_i32 s25, s44, s30
	v_add_u32_e32 v206, s24, v143
	v_lshl_add_u64 v[140:141], v[140:141], 0, s[48:49]
	s_mov_b32 m0, s25
	ds_read_b128 v[194:197], v206
	ds_read_b128 v[198:201], v206 offset:1024
	ds_read_b128 v[202:205], v206 offset:2048
	ds_read_b128 v[206:209], v206 offset:3072
	global_load_lds_dwordx4 v[140:141], off
	v_lshl_add_u64 v[140:141], v[210:211], 0, s[48:49]
	s_add_i32 m0, s25, 0x2000
	s_nop 0
	global_load_lds_dwordx4 v[140:141], off
	s_barrier
	s_waitcnt lgkmcnt(0)
	v_mfma_f32_16x16x32_bf16 v[118:121], v[194:197], v[162:165], v[118:121]
	v_mfma_f32_16x16x32_bf16 v[114:117], v[202:205], v[162:165], v[114:117]
	v_mfma_f32_16x16x32_bf16 v[102:105], v[194:197], v[170:173], v[102:105]
	v_mfma_f32_16x16x32_bf16 v[98:101], v[202:205], v[170:173], v[98:101]
	v_mfma_f32_16x16x32_bf16 v[86:89], v[194:197], v[178:181], v[86:89]
	v_mfma_f32_16x16x32_bf16 v[82:85], v[202:205], v[178:181], v[82:85]
	v_mfma_f32_16x16x32_bf16 v[70:73], v[194:197], v[186:189], v[70:73]
	v_mfma_f32_16x16x32_bf16 v[66:69], v[202:205], v[186:189], v[66:69]
	v_mfma_f32_16x16x32_bf16 v[118:121], v[198:201], v[166:169], v[118:121]
	v_mfma_f32_16x16x32_bf16 v[114:117], v[206:209], v[166:169], v[114:117]
	v_mfma_f32_16x16x32_bf16 v[102:105], v[198:201], v[174:177], v[102:105]
	v_mfma_f32_16x16x32_bf16 v[98:101], v[206:209], v[174:177], v[98:101]
	v_mfma_f32_16x16x32_bf16 v[86:89], v[198:201], v[182:185], v[86:89]
	v_mfma_f32_16x16x32_bf16 v[82:85], v[206:209], v[182:185], v[82:85]
	v_mfma_f32_16x16x32_bf16 v[70:73], v[198:201], v[190:193], v[70:73]
	v_mfma_f32_16x16x32_bf16 v[66:69], v[206:209], v[190:193], v[66:69]
	s_mov_b32 m0, s37
	v_lshl_add_u64 v[140:141], v[220:221], 0, s[48:49]
	s_barrier
	ds_read_b128 v[162:165], v145 offset:49152
	ds_read_b128 v[166:169], v145 offset:50176
	ds_read_b128 v[170:173], v145 offset:51200
	ds_read_b128 v[174:177], v145 offset:52224
	ds_read_b128 v[178:181], v145 offset:53248
	ds_read_b128 v[182:185], v145 offset:54272
	ds_read_b128 v[186:189], v145 offset:55296
	ds_read_b128 v[190:193], v145 offset:56320
	global_load_lds_dwordx4 v[140:141], off
	v_lshl_add_u64 v[140:141], v[222:223], 0, s[48:49]
	s_mov_b32 m0, s38
	s_nop 0
	global_load_lds_dwordx4 v[140:141], off
	s_barrier
; __device__ __forceinline__ unsigned cvt_pk_bf16(float lo, float hi) { f32x2_t v = {lo, hi}; bf16x2_t b = __builtin_convertvector(v, bf16x2_t); return __builtin_bit_cast(unsigned, b); }
; #define PG8_STAGE(bufoff, gbase, voff) do { _Pragma("unroll") for (int _i = 0; _i < 2; ++_i) \
;         __builtin_amdgcn_global_load_lds((const unsigned*)((const char*)(gbase) + (voff)[_i]), (LAS unsigned*)(lds + (bufoff) + ldsw + _i * 8192), 16, 0, 0); } while (0)
; #define PG8_LDA(dst, b, h) do { _Pragma("unroll") for (int m = 0; m < 4; ++m) _Pragma("unroll") for (int k = 0; k < 2; ++k) dst[m][k] = *(const LAS bf16x8*)(lds + PG8_SA(b, h) + aoff + m * 2048 + k * 1024); } while (0)
; #define PG8_MMA(ai, bj, At, Bt) do { __builtin_amdgcn_s_setprio(1); _Pragma("unroll") for (int m = 0; m < 4; ++m) _Pragma("unroll") for (int n = 0; n < 2; ++n) _Pragma("unroll") for (int k = 0; k < 2; ++k) \
;         acc[ai][bj][m][n] = __builtin_amdgcn_mfma_f32_16x16x32_bf16(Bt[n][k], At[m][k], acc[ai][bj][m][n], 0, 0, 0); __builtin_amdgcn_s_setprio(0); } while (0)
; #define PG8_BAR __builtin_amdgcn_s_barrier()
; template <class Epi, class Sched>
; __device__ __forceinline__ void gemm_phase(LAS unsigned char* lds, const Gemm g, const Sched& S, const Epi& E) {
;     ...
;             PG8_LDA(At, 1, 1); PG8_STAGE(PG8_SA(1, 0), a3, voffA);
;             PG8_BAR; PG8_WAIT_L(0); PG8_MMA(1, 0, At, B0); PG8_BAR; PG8_SCHED;
;             PG8_STAGE(PG8_SB(1, 1), b3 + hstep, voffB);
;             PG8_WAIT_V(6); PG8_BAR; PG8_MMA(1, 1, At, B1); PG8_BAR;
;     __device__ __forceinline__ void operator()(const f32x4 (&acc)[2][2][4][2], const pg8::Unit& u, int wr, int wc, int fr, int fq) const {
;     ...
;                 for (int bj = 0; bj < 2; ++bj) { f32x4 v0 = acc[ai][bj][m][0], v1 = acc[ai][bj][m][1];
;                     if (ACT == 1) {
; #pragma unroll
;                         for (int j = 0; j < 4; ++j) { float a = fmaxf(v0[j], 0.f), b = fmaxf(v1[j], 0.f); v0[j] = a * a; v1[j] = b * b; } }
;                     if (ACT == 0) { if (u.pn == (C_G / 256) && bj == 0 && wc == 0 && fq < 2) { float* gp = gate + (size_t)row * 16 + 8 * fq; *(f32x4*)gp = v0; *(f32x4*)(gp + 4) = v1; } }
;                     u32x4 w; w.x = cvt_pk_bf16(v0[0], v0[1]); w.y = cvt_pk_bf16(v0[2], v0[3]); w.z = cvt_pk_bf16(v1[0], v1[1]); w.w = cvt_pk_bf16(v1[2], v1[3]);
;                     *(u32x4*)(rowp + bj * 128) = w; } }
	s_waitcnt lgkmcnt(0)
	v_mfma_f32_16x16x32_bf16 v[62:65], v[146:149], v[162:165], v[62:65]
	v_mfma_f32_16x16x32_bf16 v[58:61], v[154:157], v[162:165], v[58:61]
	v_mfma_f32_16x16x32_bf16 v[46:49], v[146:149], v[170:173], v[46:49]
	v_mfma_f32_16x16x32_bf16 v[42:45], v[154:157], v[170:173], v[42:45]
	v_mfma_f32_16x16x32_bf16 v[30:33], v[146:149], v[178:181], v[30:33]
	v_mfma_f32_16x16x32_bf16 v[26:29], v[154:157], v[178:181], v[26:29]
	v_mfma_f32_16x16x32_bf16 v[14:17], v[146:149], v[186:189], v[14:17]
	v_mfma_f32_16x16x32_bf16 v[10:13], v[154:157], v[186:189], v[10:13]
	v_mfma_f32_16x16x32_bf16 v[62:65], v[150:153], v[166:169], v[62:65]
	v_mfma_f32_16x16x32_bf16 v[58:61], v[158:161], v[166:169], v[58:61]
	v_mfma_f32_16x16x32_bf16 v[46:49], v[150:153], v[174:177], v[46:49]
	v_mfma_f32_16x16x32_bf16 v[42:45], v[158:161], v[174:177], v[42:45]
	v_mfma_f32_16x16x32_bf16 v[30:33], v[150:153], v[182:185], v[30:33]
	v_mfma_f32_16x16x32_bf16 v[26:29], v[158:161], v[182:185], v[26:29]
	v_mfma_f32_16x16x32_bf16 v[14:17], v[150:153], v[190:193], v[14:17]
	v_mfma_f32_16x16x32_bf16 v[10:13], v[158:161], v[190:193], v[10:13]
	s_barrier
	s_add_u32 s22, s22, 0x80080
	s_addc_u32 s23, s23, 0
	s_add_i32 s24, s24, s30
	v_lshl_add_u64 v[140:141], s[22:23], 0, v[0:1]
	s_mov_b32 m0, s24
	s_nop 0
	global_load_lds_dwordx4 v[140:141], off
	v_lshl_add_u64 v[140:141], s[22:23], 0, v[130:131]
	s_add_i32 m0, s24, 0x2000
	s_nop 0
	global_load_lds_dwordx4 v[140:141], off
	s_waitcnt vmcnt(6)
	s_barrier
	v_mfma_f32_16x16x32_bf16 v[54:57], v[194:197], v[162:165], v[54:57]
	v_mfma_f32_16x16x32_bf16 v[50:53], v[202:205], v[162:165], v[50:53]
	v_mfma_f32_16x16x32_bf16 v[38:41], v[194:197], v[170:173], v[38:41]
	v_mfma_f32_16x16x32_bf16 v[34:37], v[202:205], v[170:173], v[34:37]
	v_mfma_f32_16x16x32_bf16 v[22:25], v[194:197], v[178:181], v[22:25]
	v_mfma_f32_16x16x32_bf16 v[18:21], v[202:205], v[178:181], v[18:21]
	v_mfma_f32_16x16x32_bf16 v[6:9], v[194:197], v[186:189], v[6:9]
	v_mfma_f32_16x16x32_bf16 v[2:5], v[202:205], v[186:189], v[2:5]
	v_mfma_f32_16x16x32_bf16 v[54:57], v[198:201], v[166:169], v[54:57]
	v_mfma_f32_16x16x32_bf16 v[50:53], v[206:209], v[166:169], v[50:53]
	v_mfma_f32_16x16x32_bf16 v[38:41], v[198:201], v[174:177], v[38:41]
	v_mfma_f32_16x16x32_bf16 v[34:37], v[206:209], v[174:177], v[34:37]
	v_mfma_f32_16x16x32_bf16 v[22:25], v[198:201], v[182:185], v[22:25]
	v_mfma_f32_16x16x32_bf16 v[18:21], v[206:209], v[182:185], v[18:21]
	v_mfma_f32_16x16x32_bf16 v[6:9], v[198:201], v[190:193], v[6:9]
	v_mfma_f32_16x16x32_bf16 v[2:5], v[206:209], v[190:193], v[2:5]
	s_add_i32 s43, s43, 2
	s_add_u32 s20, s20, 0x100
	s_addc_u32 s21, s21, 0
	s_add_u32 s41, s41, 0x100
	s_addc_u32 s42, s42, 0
	s_cmp_gt_u32 s43, 29
	s_barrier
	s_cbranch_scc0 .LBB0_1279
	v_lshl_add_u32 v146, s18, 8, v142
	v_lshl_or_b32 v140, s16, 8, v144
	v_ashrrev_i32_e32 v147, 31, v146
	v_ashrrev_i32_e32 v141, 31, v140
	v_lshlrev_b64 v[148:149], 14, v[146:147]
	v_max_f32_e32 v122, v122, v122
	v_max_f32_e32 v123, v123, v123
	v_lshl_add_u64 v[148:149], s[58:59], 0, v[148:149]
	v_lshlrev_b64 v[150:151], 1, v[140:141]
	v_max_f32_e32 v122, 0, v122
	v_max_f32_e32 v123, 0, v123
	v_lshl_add_u64 v[140:141], v[148:149], 0, v[150:151]
	v_pk_mul_f32 v[148:149], v[122:123], v[122:123]
	v_max_f32_e32 v123, v124, v124
	v_max_f32_e32 v126, v126, v126
	v_max_f32_e32 v127, v127, v127
	v_max_f32_e32 v122, v128, v128
	v_max_f32_e32 v124, 0, v123
	v_max_f32_e32 v123, v129, v129
	v_max_f32_e32 v125, v125, v125
	v_max_f32_e32 v126, 0, v126
	v_max_f32_e32 v127, 0, v127
	v_max_f32_e32 v122, 0, v122
	v_max_f32_e32 v123, 0, v123
	v_max_f32_e32 v125, 0, v125
	v_pk_mul_f32 v[126:127], v[126:127], v[126:127]
	v_pk_mul_f32 v[128:129], v[122:123], v[122:123]
	v_pk_mul_f32 v[152:153], v[124:125], v[124:125]
	v_max_f32_e32 v114, v114, v114
	v_max_f32_e32 v115, v115, v115
	v_cvt_pk_bf16_f32 v122, v126, v127
	v_cvt_pk_bf16_f32 v123, v128, v129
	v_cvt_pk_bf16_f32 v124, v148, v149
	v_cvt_pk_bf16_f32 v125, v152, v153
	v_max_f32_e32 v114, 0, v114
	v_max_f32_e32 v115, 0, v115
	global_store_dwordx4 v[140:141], v[122:125], off
	v_max_f32_e32 v118, v118, v118
	v_max_f32_e32 v119, v119, v119
	v_pk_mul_f32 v[122:123], v[114:115], v[114:115]
	v_max_f32_e32 v115, v116, v116
	v_max_f32_e32 v114, v120, v120
	v_max_f32_e32 v116, 0, v115
	v_max_f32_e32 v115, v121, v121
	v_max_f32_e32 v117, v117, v117
	v_max_f32_e32 v118, 0, v118
	v_max_f32_e32 v119, 0, v119
	v_max_f32_e32 v114, 0, v114
	v_max_f32_e32 v115, 0, v115
	v_max_f32_e32 v117, 0, v117
	v_pk_mul_f32 v[118:119], v[118:119], v[118:119]
	v_pk_mul_f32 v[120:121], v[114:115], v[114:115]
	v_pk_mul_f32 v[124:125], v[116:117], v[116:117]
	v_max_f32_e32 v106, v106, v106
	v_max_f32_e32 v107, v107, v107
	v_cvt_pk_bf16_f32 v114, v118, v119
	v_cvt_pk_bf16_f32 v115, v120, v121
	v_cvt_pk_bf16_f32 v116, v122, v123
	v_cvt_pk_bf16_f32 v117, v124, v125
	v_max_f32_e32 v106, 0, v106
	v_max_f32_e32 v107, 0, v107
	global_store_dwordx4 v[140:141], v[114:117], off offset:256
	v_max_f32_e32 v110, v110, v110
	v_max_f32_e32 v111, v111, v111
	v_or_b32_e32 v114, 16, v146
	v_pk_mul_f32 v[116:117], v[106:107], v[106:107]
	v_max_f32_e32 v107, v108, v108
	v_ashrrev_i32_e32 v115, 31, v114
	v_max_f32_e32 v106, v112, v112
	v_max_f32_e32 v108, 0, v107
	v_max_f32_e32 v107, v113, v113
	v_max_f32_e32 v109, v109, v109
	v_lshlrev_b64 v[114:115], 14, v[114:115]
	v_max_f32_e32 v110, 0, v110
	v_max_f32_e32 v111, 0, v111
	v_max_f32_e32 v106, 0, v106
	v_max_f32_e32 v107, 0, v107
	v_max_f32_e32 v109, 0, v109
	v_lshl_add_u64 v[114:115], s[58:59], 0, v[114:115]
	v_pk_mul_f32 v[110:111], v[110:111], v[110:111]
	v_pk_mul_f32 v[112:113], v[106:107], v[106:107]
; __device__ __forceinline__ unsigned cvt_pk_bf16(float lo, float hi) { f32x2_t v = {lo, hi}; bf16x2_t b = __builtin_convertvector(v, bf16x2_t); return __builtin_bit_cast(unsigned, b); }
;     __device__ __forceinline__ void operator()(const f32x4 (&acc)[2][2][4][2], const pg8::Unit& u, int wr, int wc, int fr, int fq) const {
;     ...
;             for (int m = 0; m < 4; ++m) { const int row = row0 + ai * 128 + m * 16; bf16_t* rowp = O + (size_t)row * ldc + col0;
; #pragma unroll
;                 for (int bj = 0; bj < 2; ++bj) { f32x4 v0 = acc[ai][bj][m][0], v1 = acc[ai][bj][m][1];
;                     if (ACT == 1) {
; #pragma unroll
;                         for (int j = 0; j < 4; ++j) { float a = fmaxf(v0[j], 0.f), b = fmaxf(v1[j], 0.f); v0[j] = a * a; v1[j] = b * b; } }
;                     if (ACT == 0) { if (u.pn == (C_G / 256) && bj == 0 && wc == 0 && fq < 2) { float* gp = gate + (size_t)row * 16 + 8 * fq; *(f32x4*)gp = v0; *(f32x4*)(gp + 4) = v1; } }
;                     u32x4 w; w.x = cvt_pk_bf16(v0[0], v0[1]); w.y = cvt_pk_bf16(v0[2], v0[3]); w.z = cvt_pk_bf16(v1[0], v1[1]); w.w = cvt_pk_bf16(v1[2], v1[3]);
;                     *(u32x4*)(rowp + bj * 128) = w; } }
	v_pk_mul_f32 v[118:119], v[108:109], v[108:109]
	v_max_f32_e32 v98, v98, v98
	v_max_f32_e32 v99, v99, v99
	v_lshl_add_u64 v[114:115], v[114:115], 0, v[150:151]
	v_cvt_pk_bf16_f32 v106, v110, v111
	v_cvt_pk_bf16_f32 v107, v112, v113
	v_cvt_pk_bf16_f32 v108, v116, v117
	v_cvt_pk_bf16_f32 v109, v118, v119
	v_max_f32_e32 v98, 0, v98
	v_max_f32_e32 v99, 0, v99
	global_store_dwordx4 v[114:115], v[106:109], off
	v_max_f32_e32 v102, v102, v102
	v_max_f32_e32 v103, v103, v103
	v_pk_mul_f32 v[106:107], v[98:99], v[98:99]
	v_max_f32_e32 v99, v100, v100
	v_max_f32_e32 v98, v104, v104
	v_max_f32_e32 v100, 0, v99
	v_max_f32_e32 v99, v105, v105
	v_max_f32_e32 v101, v101, v101
	v_max_f32_e32 v102, 0, v102
	v_max_f32_e32 v103, 0, v103
	v_max_f32_e32 v98, 0, v98
	v_max_f32_e32 v99, 0, v99
	v_max_f32_e32 v101, 0, v101
	v_pk_mul_f32 v[102:103], v[102:103], v[102:103]
	v_pk_mul_f32 v[104:105], v[98:99], v[98:99]
	v_pk_mul_f32 v[108:109], v[100:101], v[100:101]
	v_max_f32_e32 v90, v90, v90
	v_max_f32_e32 v91, v91, v91
	v_cvt_pk_bf16_f32 v98, v102, v103
	v_cvt_pk_bf16_f32 v99, v104, v105
	v_cvt_pk_bf16_f32 v100, v106, v107
	v_cvt_pk_bf16_f32 v101, v108, v109
	v_max_f32_e32 v90, 0, v90
	v_max_f32_e32 v91, 0, v91
	global_store_dwordx4 v[114:115], v[98:101], off offset:256
	v_max_f32_e32 v94, v94, v94
	v_max_f32_e32 v95, v95, v95
	v_or_b32_e32 v98, 32, v146
	v_pk_mul_f32 v[100:101], v[90:91], v[90:91]
	v_max_f32_e32 v91, v92, v92
	v_ashrrev_i32_e32 v99, 31, v98
	v_max_f32_e32 v90, v96, v96
	v_max_f32_e32 v92, 0, v91
	v_max_f32_e32 v91, v97, v97
	v_max_f32_e32 v93, v93, v93
	v_lshlrev_b64 v[98:99], 14, v[98:99]
	v_max_f32_e32 v94, 0, v94
	v_max_f32_e32 v95, 0, v95
	v_max_f32_e32 v90, 0, v90
	v_max_f32_e32 v91, 0, v91
	v_max_f32_e32 v93, 0, v93
	v_lshl_add_u64 v[98:99], s[58:59], 0, v[98:99]
	v_pk_mul_f32 v[94:95], v[94:95], v[94:95]
	v_pk_mul_f32 v[96:97], v[90:91], v[90:91]
	v_pk_mul_f32 v[102:103], v[92:93], v[92:93]
	v_max_f32_e32 v82, v82, v82
	v_max_f32_e32 v83, v83, v83
	v_lshl_add_u64 v[98:99], v[98:99], 0, v[150:151]
	v_cvt_pk_bf16_f32 v90, v94, v95
	v_cvt_pk_bf16_f32 v91, v96, v97
	v_cvt_pk_bf16_f32 v92, v100, v101
	v_cvt_pk_bf16_f32 v93, v102, v103
	v_max_f32_e32 v82, 0, v82
	v_max_f32_e32 v83, 0, v83
	global_store_dwordx4 v[98:99], v[90:93], off
	v_max_f32_e32 v86, v86, v86
	v_max_f32_e32 v87, v87, v87
	v_pk_mul_f32 v[90:91], v[82:83], v[82:83]
	v_max_f32_e32 v83, v84, v84
	v_max_f32_e32 v82, v88, v88
	v_max_f32_e32 v84, 0, v83
	v_max_f32_e32 v83, v89, v89
	v_max_f32_e32 v85, v85, v85
	v_max_f32_e32 v86, 0, v86
	v_max_f32_e32 v87, 0, v87
	v_max_f32_e32 v82, 0, v82
	v_max_f32_e32 v83, 0, v83
	v_max_f32_e32 v85, 0, v85
	v_pk_mul_f32 v[86:87], v[86:87], v[86:87]
	v_pk_mul_f32 v[88:89], v[82:83], v[82:83]
	v_pk_mul_f32 v[92:93], v[84:85], v[84:85]
	v_max_f32_e32 v74, v74, v74
	v_max_f32_e32 v75, v75, v75
	v_cvt_pk_bf16_f32 v82, v86, v87
	v_cvt_pk_bf16_f32 v83, v88, v89
	v_cvt_pk_bf16_f32 v84, v90, v91
	v_cvt_pk_bf16_f32 v85, v92, v93
	v_max_f32_e32 v74, 0, v74
	v_max_f32_e32 v75, 0, v75
	global_store_dwordx4 v[98:99], v[82:85], off offset:256
	v_max_f32_e32 v78, v78, v78
	v_max_f32_e32 v79, v79, v79
	v_or_b32_e32 v82, 48, v146
	v_pk_mul_f32 v[84:85], v[74:75], v[74:75]
	v_max_f32_e32 v75, v76, v76
	v_ashrrev_i32_e32 v83, 31, v82
	v_max_f32_e32 v74, v80, v80
	v_max_f32_e32 v76, 0, v75
	v_max_f32_e32 v75, v81, v81
	v_max_f32_e32 v77, v77, v77
	v_lshlrev_b64 v[82:83], 14, v[82:83]
	v_max_f32_e32 v78, 0, v78
	v_max_f32_e32 v79, 0, v79
	v_max_f32_e32 v74, 0, v74
	v_max_f32_e32 v75, 0, v75
	v_max_f32_e32 v77, 0, v77
	v_lshl_add_u64 v[82:83], s[58:59], 0, v[82:83]
	v_pk_mul_f32 v[78:79], v[78:79], v[78:79]
	v_pk_mul_f32 v[80:81], v[74:75], v[74:75]
	v_pk_mul_f32 v[86:87], v[76:77], v[76:77]
	v_max_f32_e32 v66, v66, v66
	v_max_f32_e32 v67, v67, v67
	v_lshl_add_u64 v[82:83], v[82:83], 0, v[150:151]
	v_cvt_pk_bf16_f32 v74, v78, v79
	v_cvt_pk_bf16_f32 v75, v80, v81
	v_cvt_pk_bf16_f32 v76, v84, v85
	v_cvt_pk_bf16_f32 v77, v86, v87
	v_max_f32_e32 v66, 0, v66
	v_max_f32_e32 v67, 0, v67
	global_store_dwordx4 v[82:83], v[74:77], off
	v_max_f32_e32 v70, v70, v70
	v_max_f32_e32 v71, v71, v71
	v_pk_mul_f32 v[74:75], v[66:67], v[66:67]
	v_max_f32_e32 v67, v68, v68
	v_max_f32_e32 v66, v72, v72
	v_max_f32_e32 v68, 0, v67
	v_max_f32_e32 v67, v73, v73
	v_max_f32_e32 v69, v69, v69
	v_max_f32_e32 v70, 0, v70
	v_max_f32_e32 v71, 0, v71
	v_max_f32_e32 v66, 0, v66
	v_max_f32_e32 v67, 0, v67
	v_max_f32_e32 v69, 0, v69
	v_pk_mul_f32 v[70:71], v[70:71], v[70:71]
	v_pk_mul_f32 v[72:73], v[66:67], v[66:67]
	v_pk_mul_f32 v[76:77], v[68:69], v[68:69]
	v_max_f32_e32 v58, v58, v58
	v_max_f32_e32 v59, v59, v59
	v_cvt_pk_bf16_f32 v66, v70, v71
	v_cvt_pk_bf16_f32 v67, v72, v73
	v_cvt_pk_bf16_f32 v68, v74, v75
	v_cvt_pk_bf16_f32 v69, v76, v77
	v_max_f32_e32 v58, 0, v58
	v_max_f32_e32 v59, 0, v59
	global_store_dwordx4 v[82:83], v[66:69], off offset:256
	v_max_f32_e32 v62, v62, v62
	v_max_f32_e32 v63, v63, v63
	v_pk_mul_f32 v[68:69], v[58:59], v[58:59]
	v_max_f32_e32 v59, v60, v60
	v_max_f32_e32 v62, 0, v62
	v_max_f32_e32 v63, 0, v63
	v_max_f32_e32 v58, v64, v64
	v_max_f32_e32 v60, 0, v59
	v_max_f32_e32 v59, v65, v65
	v_max_f32_e32 v61, v61, v61
	v_pk_mul_f32 v[62:63], v[62:63], v[62:63]
	v_max_f32_e32 v58, 0, v58
	v_max_f32_e32 v59, 0, v59
	v_max_f32_e32 v61, 0, v61
	s_mov_b32 s3, 0x200000
	v_pk_mul_f32 v[64:65], v[58:59], v[58:59]
	v_pk_mul_f32 v[70:71], v[60:61], v[60:61]
	v_cvt_pk_bf16_f32 v58, v62, v63
	v_add_co_u32_e32 v62, vcc, s3, v140
	v_max_f32_e32 v50, v50, v50
	v_max_f32_e32 v51, v51, v51
	v_cvt_pk_bf16_f32 v59, v64, v65
	v_cvt_pk_bf16_f32 v60, v68, v69
	v_cvt_pk_bf16_f32 v61, v70, v71
; __device__ __forceinline__ unsigned cvt_pk_bf16(float lo, float hi) { f32x2_t v = {lo, hi}; bf16x2_t b = __builtin_convertvector(v, bf16x2_t); return __builtin_bit_cast(unsigned, b); }
; #define PG8_WAIT_V(n) asm volatile("s_waitcnt vmcnt(" #n ")" ::: "memory")
; #define PG8_BAR __builtin_amdgcn_s_barrier()
; template <class Epi, class Sched>
; __device__ __forceinline__ void gemm_phase(LAS unsigned char* lds, const Gemm g, const Sched& S, const Epi& E) {
;     ...
;         E(acc, cur, wr, wc, fr, fq); S.done(cur);
;         if (!has_next) break;
; #pragma unroll
;         for (int a = 0; a < 2; ++a)
; #pragma unroll
;             for (int b = 0; b < 2; ++b)
; #pragma unroll
;                 for (int m = 0; m < 4; ++m)
; #pragma unroll
;                     for (int n = 0; n < 2; ++n) acc[a][b][m][n] = (f32x4){0.f, 0.f, 0.f, 0.f};
;         cur = nxt; cA = nA; cB = nB; ++ui;
;     }
;     PG8_WAIT_V(0);
;     if (wr == 0) PG8_BAR;
;     PG8_BAR;
;     __device__ __forceinline__ void operator()(const f32x4 (&acc)[2][2][4][2], const pg8::Unit& u, int wr, int wc, int fr, int fq) const {
;         const int row0 = u.pm * 256 + wr * 64 + fr; const int col0 = u.pn * 256 + wc * 32 + 8 * fq;
; #pragma unroll
;         for (int ai = 0; ai < 2; ++ai)
; #pragma unroll
;             for (int m = 0; m < 4; ++m) { const int row = row0 + ai * 128 + m * 16; bf16_t* rowp = O + (size_t)row * ldc + col0;
; #pragma unroll
;                 for (int bj = 0; bj < 2; ++bj) { f32x4 v0 = acc[ai][bj][m][0], v1 = acc[ai][bj][m][1];
;                     if (ACT == 1) {
; #pragma unroll
;                         for (int j = 0; j < 4; ++j) { float a = fmaxf(v0[j], 0.f), b = fmaxf(v1[j], 0.f); v0[j] = a * a; v1[j] = b * b; } }
;                     if (ACT == 0) { if (u.pn == (C_G / 256) && bj == 0 && wc == 0 && fq < 2) { float* gp = gate + (size_t)row * 16 + 8 * fq; *(f32x4*)gp = v0; *(f32x4*)(gp + 4) = v1; } }
;                     u32x4 w; w.x = cvt_pk_bf16(v0[0], v0[1]); w.y = cvt_pk_bf16(v0[2], v0[3]); w.z = cvt_pk_bf16(v1[0], v1[1]); w.w = cvt_pk_bf16(v1[2], v1[3]);
;                     *(u32x4*)(rowp + bj * 128) = w; } }
	v_addc_co_u32_e32 v63, vcc, 0, v141, vcc
	v_max_f32_e32 v50, 0, v50
	v_max_f32_e32 v51, 0, v51
	global_store_dwordx4 v[62:63], v[58:61], off
	v_max_f32_e32 v54, v54, v54
	v_max_f32_e32 v55, v55, v55
	v_pk_mul_f32 v[58:59], v[50:51], v[50:51]
	v_max_f32_e32 v51, v52, v52
	v_max_f32_e32 v50, v56, v56
	v_max_f32_e32 v52, 0, v51
	v_max_f32_e32 v51, v57, v57
	v_max_f32_e32 v53, v53, v53
	v_max_f32_e32 v54, 0, v54
	v_max_f32_e32 v55, 0, v55
	v_max_f32_e32 v50, 0, v50
	v_max_f32_e32 v51, 0, v51
	v_max_f32_e32 v53, 0, v53
	s_mov_b64 s[20:21], 0x200000
	v_pk_mul_f32 v[54:55], v[54:55], v[54:55]
	v_pk_mul_f32 v[56:57], v[50:51], v[50:51]
	v_pk_mul_f32 v[60:61], v[52:53], v[52:53]
	v_max_f32_e32 v42, v42, v42
	v_max_f32_e32 v43, v43, v43
	v_lshl_add_u64 v[66:67], v[140:141], 0, s[20:21]
	v_cvt_pk_bf16_f32 v50, v54, v55
	v_cvt_pk_bf16_f32 v51, v56, v57
	v_cvt_pk_bf16_f32 v52, v58, v59
	v_cvt_pk_bf16_f32 v53, v60, v61
	v_max_f32_e32 v42, 0, v42
	v_max_f32_e32 v43, 0, v43
	global_store_dwordx4 v[66:67], v[50:53], off offset:256
	v_max_f32_e32 v46, v46, v46
	v_max_f32_e32 v47, v47, v47
	v_pk_mul_f32 v[52:53], v[42:43], v[42:43]
	v_max_f32_e32 v43, v44, v44
	v_max_f32_e32 v46, 0, v46
	v_max_f32_e32 v47, 0, v47
	v_max_f32_e32 v42, v48, v48
	v_max_f32_e32 v44, 0, v43
	v_max_f32_e32 v43, v49, v49
	v_max_f32_e32 v45, v45, v45
	v_pk_mul_f32 v[46:47], v[46:47], v[46:47]
	v_max_f32_e32 v42, 0, v42
	v_max_f32_e32 v43, 0, v43
	v_max_f32_e32 v45, 0, v45
	s_mov_b32 s3, 0x240000
	v_pk_mul_f32 v[48:49], v[42:43], v[42:43]
	v_pk_mul_f32 v[54:55], v[44:45], v[44:45]
	v_cvt_pk_bf16_f32 v42, v46, v47
	v_add_co_u32_e32 v46, vcc, s3, v140
	v_max_f32_e32 v34, v34, v34
	v_max_f32_e32 v35, v35, v35
	v_cvt_pk_bf16_f32 v43, v48, v49
	v_cvt_pk_bf16_f32 v44, v52, v53
	v_cvt_pk_bf16_f32 v45, v54, v55
	v_addc_co_u32_e32 v47, vcc, 0, v141, vcc
	v_max_f32_e32 v34, 0, v34
	v_max_f32_e32 v35, 0, v35
	global_store_dwordx4 v[46:47], v[42:45], off
	v_max_f32_e32 v38, v38, v38
	v_max_f32_e32 v39, v39, v39
	v_pk_mul_f32 v[42:43], v[34:35], v[34:35]
	v_max_f32_e32 v35, v36, v36
	v_max_f32_e32 v34, v40, v40
	v_max_f32_e32 v36, 0, v35
	v_max_f32_e32 v35, v41, v41
	v_max_f32_e32 v37, v37, v37
	v_max_f32_e32 v38, 0, v38
	v_max_f32_e32 v39, 0, v39
	v_max_f32_e32 v34, 0, v34
	v_max_f32_e32 v35, 0, v35
	v_max_f32_e32 v37, 0, v37
	s_mov_b64 s[20:21], 0x240000
	v_pk_mul_f32 v[38:39], v[38:39], v[38:39]
	v_pk_mul_f32 v[40:41], v[34:35], v[34:35]
	v_pk_mul_f32 v[44:45], v[36:37], v[36:37]
	v_max_f32_e32 v26, v26, v26
	v_max_f32_e32 v27, v27, v27
	v_lshl_add_u64 v[50:51], v[140:141], 0, s[20:21]
	v_cvt_pk_bf16_f32 v34, v38, v39
	v_cvt_pk_bf16_f32 v35, v40, v41
	v_cvt_pk_bf16_f32 v36, v42, v43
	v_cvt_pk_bf16_f32 v37, v44, v45
	v_max_f32_e32 v26, 0, v26
	v_max_f32_e32 v27, 0, v27
	global_store_dwordx4 v[50:51], v[34:37], off offset:256
	v_max_f32_e32 v30, v30, v30
	v_max_f32_e32 v31, v31, v31
	v_pk_mul_f32 v[36:37], v[26:27], v[26:27]
	v_max_f32_e32 v27, v28, v28
	v_max_f32_e32 v30, 0, v30
	v_max_f32_e32 v31, 0, v31
	v_max_f32_e32 v26, v32, v32
	v_max_f32_e32 v28, 0, v27
	v_max_f32_e32 v27, v33, v33
	v_max_f32_e32 v29, v29, v29
	v_pk_mul_f32 v[30:31], v[30:31], v[30:31]
	v_max_f32_e32 v26, 0, v26
	v_max_f32_e32 v27, 0, v27
	v_max_f32_e32 v29, 0, v29
	s_mov_b32 s3, 0x280000
	v_pk_mul_f32 v[32:33], v[26:27], v[26:27]
	v_pk_mul_f32 v[38:39], v[28:29], v[28:29]
	v_cvt_pk_bf16_f32 v26, v30, v31
	v_add_co_u32_e32 v30, vcc, s3, v140
	v_max_f32_e32 v18, v18, v18
	v_max_f32_e32 v19, v19, v19
	v_cvt_pk_bf16_f32 v27, v32, v33
	v_cvt_pk_bf16_f32 v28, v36, v37
	v_cvt_pk_bf16_f32 v29, v38, v39
	v_addc_co_u32_e32 v31, vcc, 0, v141, vcc
	v_max_f32_e32 v18, 0, v18
	v_max_f32_e32 v19, 0, v19
	global_store_dwordx4 v[30:31], v[26:29], off
	v_max_f32_e32 v22, v22, v22
	v_max_f32_e32 v23, v23, v23
	v_pk_mul_f32 v[26:27], v[18:19], v[18:19]
	v_max_f32_e32 v19, v20, v20
	v_max_f32_e32 v18, v24, v24
	v_max_f32_e32 v20, 0, v19
	v_max_f32_e32 v19, v25, v25
	v_max_f32_e32 v21, v21, v21
	v_max_f32_e32 v22, 0, v22
	v_max_f32_e32 v23, 0, v23
	v_max_f32_e32 v18, 0, v18
	v_max_f32_e32 v19, 0, v19
	v_max_f32_e32 v21, 0, v21
	s_mov_b64 s[20:21], 0x280000
	v_pk_mul_f32 v[22:23], v[22:23], v[22:23]
	v_pk_mul_f32 v[24:25], v[18:19], v[18:19]
	v_pk_mul_f32 v[28:29], v[20:21], v[20:21]
	v_max_f32_e32 v10, v10, v10
	v_max_f32_e32 v11, v11, v11
	v_lshl_add_u64 v[34:35], v[140:141], 0, s[20:21]
	v_cvt_pk_bf16_f32 v18, v22, v23
	v_cvt_pk_bf16_f32 v19, v24, v25
	v_cvt_pk_bf16_f32 v20, v26, v27
	v_cvt_pk_bf16_f32 v21, v28, v29
	v_max_f32_e32 v10, 0, v10
	v_max_f32_e32 v11, 0, v11
	global_store_dwordx4 v[34:35], v[18:21], off offset:256
	v_max_f32_e32 v14, v14, v14
	v_max_f32_e32 v15, v15, v15
	v_pk_mul_f32 v[20:21], v[10:11], v[10:11]
	v_max_f32_e32 v11, v12, v12
	v_max_f32_e32 v14, 0, v14
	v_max_f32_e32 v15, 0, v15
	v_max_f32_e32 v10, v16, v16
	v_max_f32_e32 v12, 0, v11
	v_max_f32_e32 v11, v17, v17
	v_max_f32_e32 v13, v13, v13
	v_pk_mul_f32 v[14:15], v[14:15], v[14:15]
	v_max_f32_e32 v10, 0, v10
	v_max_f32_e32 v11, 0, v11
	v_max_f32_e32 v13, 0, v13
	s_mov_b32 s3, 0x2c0000
	v_pk_mul_f32 v[16:17], v[10:11], v[10:11]
	v_pk_mul_f32 v[22:23], v[12:13], v[12:13]
	v_cvt_pk_bf16_f32 v10, v14, v15
	v_add_co_u32_e32 v14, vcc, s3, v140
	v_max_f32_e32 v2, v2, v2
	v_max_f32_e32 v3, v3, v3
	v_cvt_pk_bf16_f32 v11, v16, v17
	v_cvt_pk_bf16_f32 v12, v20, v21
	v_cvt_pk_bf16_f32 v13, v22, v23
	v_addc_co_u32_e32 v15, vcc, 0, v141, vcc
	v_max_f32_e32 v2, 0, v2
	v_max_f32_e32 v3, 0, v3
	global_store_dwordx4 v[14:15], v[10:13], off
	v_max_f32_e32 v6, v6, v6
	v_max_f32_e32 v7, v7, v7
	v_pk_mul_f32 v[10:11], v[2:3], v[2:3]
	v_max_f32_e32 v3, v4, v4
	v_max_f32_e32 v2, v8, v8
	v_max_f32_e32 v4, 0, v3
	v_max_f32_e32 v3, v9, v9
	v_max_f32_e32 v5, v5, v5
	v_max_f32_e32 v6, 0, v6
	v_max_f32_e32 v7, 0, v7
	v_max_f32_e32 v2, 0, v2
	v_max_f32_e32 v3, 0, v3
	v_max_f32_e32 v5, 0, v5
	s_mov_b64 s[20:21], 0x2c0000
	v_pk_mul_f32 v[6:7], v[6:7], v[6:7]
	v_pk_mul_f32 v[8:9], v[2:3], v[2:3]
	v_pk_mul_f32 v[12:13], v[4:5], v[4:5]
	v_lshl_add_u64 v[18:19], v[140:141], 0, s[20:21]
	v_cvt_pk_bf16_f32 v2, v6, v7
	v_cvt_pk_bf16_f32 v3, v8, v9
	v_cvt_pk_bf16_f32 v4, v10, v11
	v_cvt_pk_bf16_f32 v5, v12, v13
	s_and_b64 vcc, exec, s[0:1]
	s_mov_b32 s16, s8
	s_mov_b32 s18, s10
	s_mov_b64 s[22:23], s[14:15]
	s_mov_b64 s[20:21], s[12:13]
	global_store_dwordx4 v[18:19], v[2:5], off offset:256
	s_cbranch_vccz .LBB0_1276
	s_waitcnt vmcnt(0)
	s_cmpk_gt_u32 s27, 0xff
	s_cbranch_scc1 .LBB0_1283
	s_barrier

; #define PG8_STAGE(bufoff, gbase, voff) do { _Pragma("unroll") for (int _i = 0; _i < 2; ++_i) \
;         __builtin_amdgcn_global_load_lds((const unsigned*)((const char*)(gbase) + (voff)[_i]), (LAS unsigned*)(lds + (bufoff) + ldsw + _i * 8192), 16, 0, 0); } while (0)
; #define PG8_LDA(dst, b, h) do { _Pragma("unroll") for (int m = 0; m < 4; ++m) _Pragma("unroll") for (int k = 0; k < 2; ++k) dst[m][k] = *(const LAS bf16x8*)(lds + PG8_SA(b, h) + aoff + m * 2048 + k * 1024); } while (0)
; #define PG8_LDB(dst, b, h) do { _Pragma("unroll") for (int n = 0; n < 2; ++n) _Pragma("unroll") for (int k = 0; k < 2; ++k) dst[n][k] = *(const LAS bf16x8*)(lds + PG8_SB(b, h) + boff + n * 2048 + k * 1024); } while (0)
; #define PG8_MMA(ai, bj, At, Bt) do { __builtin_amdgcn_s_setprio(1); _Pragma("unroll") for (int m = 0; m < 4; ++m) _Pragma("unroll") for (int n = 0; n < 2; ++n) _Pragma("unroll") for (int k = 0; k < 2; ++k) \
;         acc[ai][bj][m][n] = __builtin_amdgcn_mfma_f32_16x16x32_bf16(Bt[n][k], At[m][k], acc[ai][bj][m][n], 0, 0, 0); __builtin_amdgcn_s_setprio(0); } while (0)
; #define PG8_WAIT_V(n) asm volatile("s_waitcnt vmcnt(" #n ")" ::: "memory")
; #define PG8_WAIT_L(n) asm volatile("s_waitcnt lgkmcnt(" #n ")" ::: "memory")
; #define PG8_BAR __builtin_amdgcn_s_barrier()
; #define PG8_SCHED __builtin_amdgcn_sched_barrier(0)
; template <class Epi, class Sched>
; __device__ __forceinline__ void gemm_phase(LAS unsigned char* lds, const Gemm g, const Sched& S, const Epi& E) {
;     ...
;             PG8_LDB(B0, 0, 0); PG8_SCHED; PG8_LDA(At, 0, 0); PG8_STAGE(PG8_SA(1, 1), a1 + hstep, voffA);
;             PG8_WAIT_L(8); PG8_BAR; PG8_WAIT_L(0); PG8_MMA(0, 0, At, B0); PG8_BAR; PG8_SCHED;
;             PG8_LDB(B1, 0, 1); PG8_STAGE(PG8_SB(0, 0), b2, voffB);
;             PG8_BAR; PG8_WAIT_L(0); PG8_MMA(0, 1, At, B1); PG8_BAR;
;             PG8_LDA(At, 0, 1); PG8_STAGE(PG8_SA(0, 0), a2, voffA);
;             PG8_BAR; PG8_WAIT_L(0); PG8_MMA(1, 0, At, B0); PG8_BAR; PG8_SCHED;
;             PG8_STAGE(PG8_SB(0, 1), b2 + hstep, voffB);
;             PG8_WAIT_V(6); PG8_BAR; PG8_MMA(1, 1, At, B1); PG8_BAR;
.LBB0_1343:
	s_nop 0
	v_add_u32_e32 v136, s42, v139
	ds_read_b128 v[142:145], v136
	ds_read_b128 v[146:149], v136 offset:1024
	ds_read_b128 v[150:153], v136 offset:2048
	ds_read_b128 v[154:157], v136 offset:3072
	s_add_u32 s18, s16, 0x100
	s_addc_u32 s19, s17, 0
	s_cmpk_eq_i32 s40, 0x7c
	s_cselect_b32 s23, s3, s19
	s_cselect_b32 s22, s7, s18
	s_cselect_b32 s21, s5, s39
	s_cselect_b32 s20, s37, s38
	v_lshl_add_u64 v[136:137], s[16:17], 0, v[132:133]
	s_add_i32 m0, s13, 0xc000
	ds_read_b128 v[158:161], v141
	ds_read_b128 v[162:165], v141 offset:1024
	ds_read_b128 v[166:169], v141 offset:2048
	ds_read_b128 v[170:173], v141 offset:3072
	ds_read_b128 v[174:177], v141 offset:4096
	ds_read_b128 v[178:181], v141 offset:5120
	ds_read_b128 v[182:185], v141 offset:6144
	ds_read_b128 v[186:189], v141 offset:7168
	global_load_lds_dwordx4 v[136:137], off
	v_lshl_add_u64 v[136:137], s[16:17], 0, v[134:135]
	s_add_i32 m0, s13, 0xe000
	s_nop 0
	global_load_lds_dwordx4 v[136:137], off
	s_waitcnt lgkmcnt(8)
	s_barrier
	s_waitcnt lgkmcnt(0)
	v_mfma_f32_16x16x32_bf16 v[126:129], v[142:145], v[158:161], v[126:129]
	v_mfma_f32_16x16x32_bf16 v[122:125], v[150:153], v[158:161], v[122:125]
	v_mfma_f32_16x16x32_bf16 v[110:113], v[142:145], v[166:169], v[110:113]
	v_mfma_f32_16x16x32_bf16 v[106:109], v[150:153], v[166:169], v[106:109]
	v_mfma_f32_16x16x32_bf16 v[94:97], v[142:145], v[174:177], v[94:97]
	v_mfma_f32_16x16x32_bf16 v[90:93], v[150:153], v[174:177], v[90:93]
	v_mfma_f32_16x16x32_bf16 v[78:81], v[142:145], v[182:185], v[78:81]
	v_mfma_f32_16x16x32_bf16 v[74:77], v[150:153], v[182:185], v[74:77]
	v_mfma_f32_16x16x32_bf16 v[126:129], v[146:149], v[162:165], v[126:129]
	v_mfma_f32_16x16x32_bf16 v[122:125], v[154:157], v[162:165], v[122:125]
	v_mfma_f32_16x16x32_bf16 v[110:113], v[146:149], v[170:173], v[110:113]
	v_mfma_f32_16x16x32_bf16 v[106:109], v[154:157], v[170:173], v[106:109]
	v_mfma_f32_16x16x32_bf16 v[94:97], v[146:149], v[178:181], v[94:97]
	v_mfma_f32_16x16x32_bf16 v[90:93], v[154:157], v[178:181], v[90:93]
	v_mfma_f32_16x16x32_bf16 v[78:81], v[146:149], v[186:189], v[78:81]
	v_mfma_f32_16x16x32_bf16 v[74:77], v[154:157], v[186:189], v[74:77]
	s_barrier
	s_add_i32 s41, 0, 0x14000
	v_add_u32_e32 v136, s41, v139
	s_add_i32 s16, s42, s28
	ds_read_b128 v[190:193], v136
	ds_read_b128 v[194:197], v136 offset:1024
	ds_read_b128 v[198:201], v136 offset:2048
	ds_read_b128 v[202:205], v136 offset:3072
	v_lshl_add_u64 v[136:137], s[20:21], 0, v[0:1]
	s_mov_b32 m0, s16
	v_lshl_add_u64 v[206:207], s[20:21], 0, v[130:131]
	global_load_lds_dwordx4 v[136:137], off
	s_add_i32 m0, s16, 0x2000
	s_nop 0
	global_load_lds_dwordx4 v[206:207], off
	s_barrier
	s_waitcnt lgkmcnt(0)
	v_mfma_f32_16x16x32_bf16 v[118:121], v[190:193], v[158:161], v[118:121]
	v_mfma_f32_16x16x32_bf16 v[114:117], v[198:201], v[158:161], v[114:117]
	v_mfma_f32_16x16x32_bf16 v[102:105], v[190:193], v[166:169], v[102:105]
	v_mfma_f32_16x16x32_bf16 v[98:101], v[198:201], v[166:169], v[98:101]
	v_mfma_f32_16x16x32_bf16 v[86:89], v[190:193], v[174:177], v[86:89]
	v_mfma_f32_16x16x32_bf16 v[82:85], v[198:201], v[174:177], v[82:85]
	v_mfma_f32_16x16x32_bf16 v[70:73], v[190:193], v[182:185], v[70:73]
	v_mfma_f32_16x16x32_bf16 v[66:69], v[198:201], v[182:185], v[66:69]
	v_mfma_f32_16x16x32_bf16 v[118:121], v[194:197], v[162:165], v[118:121]
	v_mfma_f32_16x16x32_bf16 v[114:117], v[202:205], v[162:165], v[114:117]
	v_mfma_f32_16x16x32_bf16 v[102:105], v[194:197], v[170:173], v[102:105]
	v_mfma_f32_16x16x32_bf16 v[98:101], v[202:205], v[170:173], v[98:101]
	v_mfma_f32_16x16x32_bf16 v[86:89], v[194:197], v[178:181], v[86:89]
	v_mfma_f32_16x16x32_bf16 v[82:85], v[202:205], v[178:181], v[82:85]
	v_mfma_f32_16x16x32_bf16 v[70:73], v[194:197], v[186:189], v[70:73]
	v_mfma_f32_16x16x32_bf16 v[66:69], v[202:205], v[186:189], v[66:69]
	s_mov_b32 m0, s13
	v_lshl_add_u64 v[208:209], s[22:23], 0, v[0:1]
	s_barrier
	ds_read_b128 v[158:161], v141 offset:16384
	ds_read_b128 v[162:165], v141 offset:17408
	ds_read_b128 v[166:169], v141 offset:18432
	ds_read_b128 v[170:173], v141 offset:19456
	ds_read_b128 v[174:177], v141 offset:20480
	ds_read_b128 v[178:181], v141 offset:21504
	ds_read_b128 v[182:185], v141 offset:22528
	ds_read_b128 v[186:189], v141 offset:23552
	global_load_lds_dwordx4 v[208:209], off
	v_lshl_add_u64 v[210:211], s[22:23], 0, v[130:131]
	s_mov_b32 m0, s15
	s_nop 0
	global_load_lds_dwordx4 v[210:211], off
	s_barrier
	s_waitcnt lgkmcnt(0)
	v_mfma_f32_16x16x32_bf16 v[62:65], v[142:145], v[158:161], v[62:65]
	v_mfma_f32_16x16x32_bf16 v[58:61], v[150:153], v[158:161], v[58:61]
	v_mfma_f32_16x16x32_bf16 v[46:49], v[142:145], v[166:169], v[46:49]
	v_mfma_f32_16x16x32_bf16 v[42:45], v[150:153], v[166:169], v[42:45]
	v_mfma_f32_16x16x32_bf16 v[30:33], v[142:145], v[174:177], v[30:33]
	v_mfma_f32_16x16x32_bf16 v[26:29], v[150:153], v[174:177], v[26:29]
	v_mfma_f32_16x16x32_bf16 v[14:17], v[142:145], v[182:185], v[14:17]
	v_mfma_f32_16x16x32_bf16 v[10:13], v[150:153], v[182:185], v[10:13]
	v_mfma_f32_16x16x32_bf16 v[62:65], v[146:149], v[162:165], v[62:65]
	v_mfma_f32_16x16x32_bf16 v[58:61], v[154:157], v[162:165], v[58:61]
	v_mfma_f32_16x16x32_bf16 v[46:49], v[146:149], v[170:173], v[46:49]
	v_mfma_f32_16x16x32_bf16 v[42:45], v[154:157], v[170:173], v[42:45]
	v_mfma_f32_16x16x32_bf16 v[30:33], v[146:149], v[178:181], v[30:33]
	v_mfma_f32_16x16x32_bf16 v[26:29], v[154:157], v[178:181], v[26:29]
	v_mfma_f32_16x16x32_bf16 v[14:17], v[146:149], v[186:189], v[14:17]
	v_mfma_f32_16x16x32_bf16 v[10:13], v[154:157], v[186:189], v[10:13]
	s_barrier
; #define PG8_STAGE(bufoff, gbase, voff) do { _Pragma("unroll") for (int _i = 0; _i < 2; ++_i) \
;         __builtin_amdgcn_global_load_lds((const unsigned*)((const char*)(gbase) + (voff)[_i]), (LAS unsigned*)(lds + (bufoff) + ldsw + _i * 8192), 16, 0, 0); } while (0)
; #define PG8_LDA(dst, b, h) do { _Pragma("unroll") for (int m = 0; m < 4; ++m) _Pragma("unroll") for (int k = 0; k < 2; ++k) dst[m][k] = *(const LAS bf16x8*)(lds + PG8_SA(b, h) + aoff + m * 2048 + k * 1024); } while (0)
; #define PG8_LDB(dst, b, h) do { _Pragma("unroll") for (int n = 0; n < 2; ++n) _Pragma("unroll") for (int k = 0; k < 2; ++k) dst[n][k] = *(const LAS bf16x8*)(lds + PG8_SB(b, h) + boff + n * 2048 + k * 1024); } while (0)
; #define PG8_MMA(ai, bj, At, Bt) do { __builtin_amdgcn_s_setprio(1); _Pragma("unroll") for (int m = 0; m < 4; ++m) _Pragma("unroll") for (int n = 0; n < 2; ++n) _Pragma("unroll") for (int k = 0; k < 2; ++k) \
;         acc[ai][bj][m][n] = __builtin_amdgcn_mfma_f32_16x16x32_bf16(Bt[n][k], At[m][k], acc[ai][bj][m][n], 0, 0, 0); __builtin_amdgcn_s_setprio(0); } while (0)
; #define PG8_WAIT_V(n) asm volatile("s_waitcnt vmcnt(" #n ")" ::: "memory")
; #define PG8_WAIT_L(n) asm volatile("s_waitcnt lgkmcnt(" #n ")" ::: "memory")
; #define PG8_BAR __builtin_amdgcn_s_barrier()
; #define PG8_SCHED __builtin_amdgcn_sched_barrier(0)
; template <class Epi, class Sched>
; __device__ __forceinline__ void gemm_phase(LAS unsigned char* lds, const Gemm g, const Sched& S, const Epi& E) {
;     ...
;             PG8_STAGE(PG8_SB(0, 1), b2 + hstep, voffB);
;             PG8_WAIT_V(6); PG8_BAR; PG8_MMA(1, 1, At, B1); PG8_BAR;
;             PG8_LDB(B0, 1, 0); PG8_SCHED; PG8_LDA(At, 1, 0); PG8_STAGE(PG8_SA(0, 1), a2 + hstep, voffA);
;             PG8_WAIT_L(8); PG8_BAR; PG8_WAIT_L(0); PG8_MMA(0, 0, At, B0); PG8_BAR; PG8_SCHED;
;             PG8_LDB(B1, 1, 1); PG8_STAGE(PG8_SB(1, 0), b3, voffB);
;             PG8_BAR; PG8_WAIT_L(0); PG8_MMA(0, 1, At, B1); PG8_BAR;
;             PG8_LDA(At, 1, 1); PG8_STAGE(PG8_SA(1, 0), a3, voffA);
;             PG8_BAR; PG8_WAIT_L(0); PG8_MMA(1, 0, At, B0); PG8_BAR; PG8_SCHED;
	s_add_u32 s16, s20, 0x200000
	s_addc_u32 s17, s21, 0
	s_add_i32 s41, s41, s28
	v_lshl_add_u64 v[142:143], s[16:17], 0, v[0:1]
	s_mov_b32 m0, s41
	s_nop 0
	global_load_lds_dwordx4 v[142:143], off
	v_lshl_add_u64 v[142:143], s[16:17], 0, v[130:131]
	s_add_i32 m0, s41, 0x2000
	s_nop 0
	global_load_lds_dwordx4 v[142:143], off
	s_waitcnt vmcnt(6)
	s_barrier
	v_mfma_f32_16x16x32_bf16 v[54:57], v[190:193], v[158:161], v[54:57]
	v_mfma_f32_16x16x32_bf16 v[50:53], v[198:201], v[158:161], v[50:53]
	v_mfma_f32_16x16x32_bf16 v[38:41], v[190:193], v[166:169], v[38:41]
	v_mfma_f32_16x16x32_bf16 v[34:37], v[198:201], v[166:169], v[34:37]
	v_mfma_f32_16x16x32_bf16 v[22:25], v[190:193], v[174:177], v[22:25]
	v_mfma_f32_16x16x32_bf16 v[18:21], v[198:201], v[174:177], v[18:21]
	v_mfma_f32_16x16x32_bf16 v[6:9], v[190:193], v[182:185], v[6:9]
	v_mfma_f32_16x16x32_bf16 v[2:5], v[198:201], v[182:185], v[2:5]
	v_mfma_f32_16x16x32_bf16 v[54:57], v[194:197], v[162:165], v[54:57]
	v_mfma_f32_16x16x32_bf16 v[50:53], v[202:205], v[162:165], v[50:53]
	v_mfma_f32_16x16x32_bf16 v[38:41], v[194:197], v[170:173], v[38:41]
	v_mfma_f32_16x16x32_bf16 v[34:37], v[202:205], v[170:173], v[34:37]
	v_mfma_f32_16x16x32_bf16 v[22:25], v[194:197], v[178:181], v[22:25]
	v_mfma_f32_16x16x32_bf16 v[18:21], v[202:205], v[178:181], v[18:21]
	v_mfma_f32_16x16x32_bf16 v[6:9], v[194:197], v[186:189], v[6:9]
	v_mfma_f32_16x16x32_bf16 v[2:5], v[202:205], v[186:189], v[2:5]
	s_add_i32 s41, 0, 0x18000
	v_add_u32_e32 v154, s41, v139
	s_barrier
	ds_read_b128 v[142:145], v154
	ds_read_b128 v[146:149], v154 offset:1024
	ds_read_b128 v[150:153], v154 offset:2048
	ds_read_b128 v[154:157], v154 offset:3072
	s_add_u32 s16, s22, 0x200000
	s_addc_u32 s17, s23, 0
	s_mov_b32 m0, s29
	v_lshl_add_u64 v[190:191], s[16:17], 0, v[0:1]
	ds_read_b128 v[158:161], v141 offset:32768
	ds_read_b128 v[162:165], v141 offset:33792
	ds_read_b128 v[166:169], v141 offset:34816
	ds_read_b128 v[170:173], v141 offset:35840
	ds_read_b128 v[174:177], v141 offset:36864
	ds_read_b128 v[178:181], v141 offset:37888
	ds_read_b128 v[182:185], v141 offset:38912
	ds_read_b128 v[186:189], v141 offset:39936
	global_load_lds_dwordx4 v[190:191], off
	v_lshl_add_u64 v[190:191], s[16:17], 0, v[130:131]
	s_mov_b32 m0, s30
	s_nop 0
	global_load_lds_dwordx4 v[190:191], off
	s_waitcnt lgkmcnt(8)
	s_barrier
	s_waitcnt lgkmcnt(0)
	v_mfma_f32_16x16x32_bf16 v[126:129], v[142:145], v[158:161], v[126:129]
	v_mfma_f32_16x16x32_bf16 v[122:125], v[150:153], v[158:161], v[122:125]
	v_mfma_f32_16x16x32_bf16 v[110:113], v[142:145], v[166:169], v[110:113]
	v_mfma_f32_16x16x32_bf16 v[106:109], v[150:153], v[166:169], v[106:109]
	v_mfma_f32_16x16x32_bf16 v[94:97], v[142:145], v[174:177], v[94:97]
	v_mfma_f32_16x16x32_bf16 v[90:93], v[150:153], v[174:177], v[90:93]
	v_mfma_f32_16x16x32_bf16 v[78:81], v[142:145], v[182:185], v[78:81]
	v_mfma_f32_16x16x32_bf16 v[74:77], v[150:153], v[182:185], v[74:77]
	v_mfma_f32_16x16x32_bf16 v[126:129], v[146:149], v[162:165], v[126:129]
	v_mfma_f32_16x16x32_bf16 v[122:125], v[154:157], v[162:165], v[122:125]
	v_mfma_f32_16x16x32_bf16 v[110:113], v[146:149], v[170:173], v[110:113]
	v_mfma_f32_16x16x32_bf16 v[106:109], v[154:157], v[170:173], v[106:109]
	v_mfma_f32_16x16x32_bf16 v[94:97], v[146:149], v[178:181], v[94:97]
	v_mfma_f32_16x16x32_bf16 v[90:93], v[154:157], v[178:181], v[90:93]
	v_mfma_f32_16x16x32_bf16 v[78:81], v[146:149], v[186:189], v[78:81]
	v_mfma_f32_16x16x32_bf16 v[74:77], v[154:157], v[186:189], v[74:77]
	s_barrier
	s_add_i32 s22, 0, 0x1c000
	s_add_i32 s16, s41, s28
	v_add_u32_e32 v202, s22, v139
	v_lshl_add_u64 v[136:137], v[136:137], 0, s[44:45]
	s_mov_b32 m0, s16
	ds_read_b128 v[190:193], v202
	ds_read_b128 v[194:197], v202 offset:1024
	ds_read_b128 v[198:201], v202 offset:2048
	ds_read_b128 v[202:205], v202 offset:3072
	global_load_lds_dwordx4 v[136:137], off
	v_lshl_add_u64 v[136:137], v[206:207], 0, s[44:45]
	s_add_i32 m0, s16, 0x2000
	s_nop 0
	global_load_lds_dwordx4 v[136:137], off
	s_barrier
	s_waitcnt lgkmcnt(0)
	v_mfma_f32_16x16x32_bf16 v[118:121], v[190:193], v[158:161], v[118:121]
	v_mfma_f32_16x16x32_bf16 v[114:117], v[198:201], v[158:161], v[114:117]
	v_mfma_f32_16x16x32_bf16 v[102:105], v[190:193], v[166:169], v[102:105]
	v_mfma_f32_16x16x32_bf16 v[98:101], v[198:201], v[166:169], v[98:101]
	v_mfma_f32_16x16x32_bf16 v[86:89], v[190:193], v[174:177], v[86:89]
	v_mfma_f32_16x16x32_bf16 v[82:85], v[198:201], v[174:177], v[82:85]
	v_mfma_f32_16x16x32_bf16 v[70:73], v[190:193], v[182:185], v[70:73]
	v_mfma_f32_16x16x32_bf16 v[66:69], v[198:201], v[182:185], v[66:69]
	v_mfma_f32_16x16x32_bf16 v[118:121], v[194:197], v[162:165], v[118:121]
	v_mfma_f32_16x16x32_bf16 v[114:117], v[202:205], v[162:165], v[114:117]
	v_mfma_f32_16x16x32_bf16 v[102:105], v[194:197], v[170:173], v[102:105]
	v_mfma_f32_16x16x32_bf16 v[98:101], v[202:205], v[170:173], v[98:101]
	v_mfma_f32_16x16x32_bf16 v[86:89], v[194:197], v[178:181], v[86:89]
	v_mfma_f32_16x16x32_bf16 v[82:85], v[202:205], v[178:181], v[82:85]
	v_mfma_f32_16x16x32_bf16 v[70:73], v[194:197], v[186:189], v[70:73]
	v_mfma_f32_16x16x32_bf16 v[66:69], v[202:205], v[186:189], v[66:69]
	s_mov_b32 m0, s34
	v_lshl_add_u64 v[136:137], v[208:209], 0, s[44:45]
	s_barrier
; #define PG8_STAGE(bufoff, gbase, voff) do { _Pragma("unroll") for (int _i = 0; _i < 2; ++_i) \
;         __builtin_amdgcn_global_load_lds((const unsigned*)((const char*)(gbase) + (voff)[_i]), (LAS unsigned*)(lds + (bufoff) + ldsw + _i * 8192), 16, 0, 0); } while (0)
; #define PG8_LDA(dst, b, h) do { _Pragma("unroll") for (int m = 0; m < 4; ++m) _Pragma("unroll") for (int k = 0; k < 2; ++k) dst[m][k] = *(const LAS bf16x8*)(lds + PG8_SA(b, h) + aoff + m * 2048 + k * 1024); } while (0)
; #define PG8_MMA(ai, bj, At, Bt) do { __builtin_amdgcn_s_setprio(1); _Pragma("unroll") for (int m = 0; m < 4; ++m) _Pragma("unroll") for (int n = 0; n < 2; ++n) _Pragma("unroll") for (int k = 0; k < 2; ++k) \
;         acc[ai][bj][m][n] = __builtin_amdgcn_mfma_f32_16x16x32_bf16(Bt[n][k], At[m][k], acc[ai][bj][m][n], 0, 0, 0); __builtin_amdgcn_s_setprio(0); } while (0)
; template <class Epi, class Sched>
; __device__ __forceinline__ void gemm_phase(LAS unsigned char* lds, const Gemm g, const Sched& S, const Epi& E) {
;     ...
;             PG8_LDA(At, 1, 1); PG8_STAGE(PG8_SA(1, 0), a3, voffA);
;             PG8_BAR; PG8_WAIT_L(0); PG8_MMA(1, 0, At, B0); PG8_BAR; PG8_SCHED;
;             PG8_STAGE(PG8_SB(1, 1), b3 + hstep, voffB);
;             PG8_WAIT_V(6); PG8_BAR; PG8_MMA(1, 1, At, B1); PG8_BAR;
;     __device__ __forceinline__ void operator()(const f32x4 (&acc)[2][2][4][2], const pg8::Unit& u, int wr, int wc, int fr, int fq) const {
;         const int row0 = u.pm * 256 + wr * 64 + fr; const int col0 = u.pn * 256 + wc * 32 + 4 * fq;
; #pragma unroll
;         for (int ai = 0; ai < 2; ++ai)
; #pragma unroll
;             for (int m = 0; m < 4; ++m) { const int row = row0 + ai * 128 + m * 16;
;                 const float* ip; float* op; int b;
;                 if (row < ML_ROWS) { b = row >> 11; ip = xi + (size_t)row * D; op = xo + (size_t)row * D; }
;                 else { b = 8; ip = ci + (size_t)(row - ML_ROWS) * D; op = co + (size_t)(row - ML_ROWS) * D; }
;                 const float* gp = mod + (size_t)b * 12288 + slot * 2048;
; #pragma unroll
;                 for (int bj = 0; bj < 2; ++bj)
; #pragma unroll
;                     for (int n = 0; n < 2; ++n) { const int c = col0 + bj * 128 + n * 16;
;                         const f32x4 r = *(const f32x4*)(ip + c), g = *(const f32x4*)(gp + c);
;                         *(f32x4*)(op + c) = r + g * acc[ai][bj][m][n]; } }
	ds_read_b128 v[158:161], v141 offset:49152
	ds_read_b128 v[162:165], v141 offset:50176
	ds_read_b128 v[166:169], v141 offset:51200
	ds_read_b128 v[170:173], v141 offset:52224
	ds_read_b128 v[174:177], v141 offset:53248
	ds_read_b128 v[178:181], v141 offset:54272
	ds_read_b128 v[182:185], v141 offset:55296
	ds_read_b128 v[186:189], v141 offset:56320
	global_load_lds_dwordx4 v[136:137], off
	v_lshl_add_u64 v[136:137], v[210:211], 0, s[44:45]
	s_mov_b32 m0, s35
	s_nop 0
	global_load_lds_dwordx4 v[136:137], off
	s_barrier
	s_waitcnt lgkmcnt(0)
	v_mfma_f32_16x16x32_bf16 v[62:65], v[142:145], v[158:161], v[62:65]
	v_mfma_f32_16x16x32_bf16 v[58:61], v[150:153], v[158:161], v[58:61]
	v_mfma_f32_16x16x32_bf16 v[46:49], v[142:145], v[166:169], v[46:49]
	v_mfma_f32_16x16x32_bf16 v[42:45], v[150:153], v[166:169], v[42:45]
	v_mfma_f32_16x16x32_bf16 v[30:33], v[142:145], v[174:177], v[30:33]
	v_mfma_f32_16x16x32_bf16 v[26:29], v[150:153], v[174:177], v[26:29]
	v_mfma_f32_16x16x32_bf16 v[14:17], v[142:145], v[182:185], v[14:17]
	v_mfma_f32_16x16x32_bf16 v[10:13], v[150:153], v[182:185], v[10:13]
	v_mfma_f32_16x16x32_bf16 v[62:65], v[146:149], v[162:165], v[62:65]
	v_mfma_f32_16x16x32_bf16 v[58:61], v[154:157], v[162:165], v[58:61]
	v_mfma_f32_16x16x32_bf16 v[46:49], v[146:149], v[170:173], v[46:49]
	v_mfma_f32_16x16x32_bf16 v[42:45], v[154:157], v[170:173], v[42:45]
	v_mfma_f32_16x16x32_bf16 v[30:33], v[146:149], v[178:181], v[30:33]
	v_mfma_f32_16x16x32_bf16 v[26:29], v[154:157], v[178:181], v[26:29]
	v_mfma_f32_16x16x32_bf16 v[14:17], v[146:149], v[186:189], v[14:17]
	v_mfma_f32_16x16x32_bf16 v[10:13], v[154:157], v[186:189], v[10:13]
	s_barrier
	s_add_u32 s16, s20, 0x200080
	s_addc_u32 s17, s21, 0
	s_add_i32 s20, s22, s28
	v_lshl_add_u64 v[136:137], s[16:17], 0, v[0:1]
	s_mov_b32 m0, s20
	s_nop 0
	global_load_lds_dwordx4 v[136:137], off
	v_lshl_add_u64 v[136:137], s[16:17], 0, v[130:131]
	s_add_i32 m0, s20, 0x2000
	s_nop 0
	global_load_lds_dwordx4 v[136:137], off
	s_waitcnt vmcnt(6)
	s_barrier
	v_mfma_f32_16x16x32_bf16 v[54:57], v[190:193], v[158:161], v[54:57]
	v_mfma_f32_16x16x32_bf16 v[50:53], v[198:201], v[158:161], v[50:53]
	v_mfma_f32_16x16x32_bf16 v[38:41], v[190:193], v[166:169], v[38:41]
	v_mfma_f32_16x16x32_bf16 v[34:37], v[198:201], v[166:169], v[34:37]
	v_mfma_f32_16x16x32_bf16 v[22:25], v[190:193], v[174:177], v[22:25]
	v_mfma_f32_16x16x32_bf16 v[18:21], v[198:201], v[174:177], v[18:21]
	v_mfma_f32_16x16x32_bf16 v[6:9], v[190:193], v[182:185], v[6:9]
	v_mfma_f32_16x16x32_bf16 v[2:5], v[198:201], v[182:185], v[2:5]
	v_mfma_f32_16x16x32_bf16 v[54:57], v[194:197], v[162:165], v[54:57]
	v_mfma_f32_16x16x32_bf16 v[50:53], v[202:205], v[162:165], v[50:53]
	v_mfma_f32_16x16x32_bf16 v[38:41], v[194:197], v[170:173], v[38:41]
	v_mfma_f32_16x16x32_bf16 v[34:37], v[202:205], v[170:173], v[34:37]
	v_mfma_f32_16x16x32_bf16 v[22:25], v[194:197], v[178:181], v[22:25]
	v_mfma_f32_16x16x32_bf16 v[18:21], v[202:205], v[178:181], v[18:21]
	v_mfma_f32_16x16x32_bf16 v[6:9], v[194:197], v[186:189], v[6:9]
	v_mfma_f32_16x16x32_bf16 v[2:5], v[202:205], v[186:189], v[2:5]
	s_add_i32 s40, s40, 2
	s_add_u32 s38, s38, 0x100
	s_addc_u32 s39, s39, 0
	s_cmpk_gt_u32 s40, 0x7d
	s_mov_b64 s[16:17], s[18:19]
	s_barrier
	s_cbranch_scc0 .LBB0_1343
	s_lshl_b32 s3, s14, 8
	s_add_i32 s3, s3, s31
	v_readlane_b32 s40, v251, 0
	v_readlane_b32 s41, v251, 1
	v_readlane_b32 s42, v251, 2
	v_readlane_b32 s43, v251, 3
	v_readlane_b32 s44, v251, 4
	v_readlane_b32 s45, v251, 5
	v_readlane_b32 s46, v251, 6
	v_readlane_b32 s47, v251, 7
	v_readlane_b32 s18, v254, 2
	v_readlane_b32 s19, v254, 3
	s_add_i32 s5, s3, 0xffffc000
	s_ashr_i32 s7, s3, 11
	s_cmpk_lt_i32 s3, 0x4000
	s_cselect_b32 s20, s42, s60
	s_cselect_b32 s21, s43, s61
	s_cselect_b32 s5, s3, s5
	s_cselect_b32 s7, s7, 8
	s_mul_i32 s7, s7, 0xc000
	s_add_u32 s18, s18, s7
	s_addc_u32 s19, s19, 0
	s_add_u32 s18, s18, 0xa000
	s_addc_u32 s19, s19, 0
	v_add_u32_e32 v136, s5, v138
	v_lshl_or_b32 v137, s12, 8, v140
	v_lshlrev_b32_e32 v137, 2, v137
	v_lshl_or_b32 v136, v136, 13, v137
	s_mov_b32 s12, s4
	s_mov_b32 s14, s6
	s_cmp_lg_u32 s36, 3
	s_cbranch_scc1 .Lsk_normal
	v_readlane_b32 s5, v253, 24
	s_cmpk_lg_u32 s46, 0x100
	s_cbranch_scc1 .Lsk_normal
	s_cmpk_lg_u32 s5, 0x240
	s_cbranch_scc1 .Lsk_normal
	s_and_b32 s7, s54, 3
	s_lshr_b32 s5, s54, 2
	s_lshr_b32 s3, s24, 6
	s_lshl_b32 s23, s5, 3
	s_add_i32 s23, s23, s3
	s_lshl_b32 s23, s23, 2
	v_readlane_b32 s38, v251, 10
	v_readlane_b32 s39, v251, 11
	s_add_u32 s38, s38, s23
	s_addc_u32 s39, s39, 0
	s_add_u32 s38, s38, 0x3700
	s_addc_u32 s39, s39, 0
	v_readlane_b32 s16, v251, 4
	v_readlane_b32 s17, v251, 5
	s_lshl_b32 s5, s5, 20
	s_add_u32 s16, s16, 0x24000000
	s_addc_u32 s17, s17, 0
	s_add_u32 s16, s16, s5
	s_addc_u32 s17, s17, 0
	v_add_u32_e32 v142, s31, v138
	v_lshlrev_b32_e32 v143, 2, v140
	v_lshl_or_b32 v142, v142, 10, v143
	global_load_dwordx4 v[146:149], v137, s[18:19]
	global_load_dwordx4 v[150:153], v137, s[18:19] offset:64
	global_load_dwordx4 v[154:157], v137, s[18:19] offset:512
	global_load_dwordx4 v[158:161], v137, s[18:19] offset:576
	s_cmp_eq_u32 s7, 1
	s_cbranch_scc1 .Lsk_v1
	s_cmp_eq_u32 s7, 2
	s_cbranch_scc1 .Lsk_v2
	s_cmp_eq_u32 s7, 3
	s_cbranch_scc1 .Lsk_v3
